# up-GEMM epilogue stores: 24-bit multiply + 32-bit shift-add offset with SGPR base instead of 64-bit mad chain (16 sites); 64-bit zero fills of exchange registers
# speedup vs baseline: 1.0055x; 1.0015x over previous
; #define PG8_LAS __attribute__((address_space(3)))
; __device__ __forceinline__ unsigned cvt_pk_bf16(float lo, float hi) { unsigned r; asm volatile("v_cvt_pk_bf16_f32 %0, %1, %2" : "=v"(r) : "v"(lo), "v"(hi)); return r; }
;     __device__ __forceinline__ void operator()(const f32x4 (&acc)[2][2][4][2], const Unit& u, int wr, int wc, int fr, int fq) const {
;     ...
;             for (int ai = 0; ai < 2; ++ai) {
;                 f32x4 pr1[2] = {zero4, zero4}, pr2[2] = {zero4, zero4};
;                 const bool hasprev = (wr == 1) || (ai == 1);
;                 const int pg = (wr == 1) ? ai * 2 : (ai - 1) * 2 + 1;
;                 if (hasprev && fr < 2) {
; #pragma unroll
;                     for (int bj = 0; bj < 2; ++bj) {
;                         pr2[bj] = *(const PG8_LAS f32x4*)(xch + ((pg * 2 + fr) * 256 + bj * 128 + colx + n * 4));
;                         pr1[bj] = *(const PG8_LAS f32x4*)(xch + ((pg * 2 + 1) * 256 + bj * 128 + colx + n * 4)); }
;                 }
; #pragma unroll
;                 for (int m = 0; m < 4; ++m) {
;                     f32x4 cur[2] = {acc[ai][0][m][n] * r2v[ai][m], acc[ai][1][m][n] * r2v[ai][m]};
;                     if (first && ai == 0 && wr == 0 && m == 0 && fr < 2) { cur[0] = zero4; cur[1] = zero4; }
;                     f32x4 r1[2], r2[2], av[2];
; #pragma unroll
;                     for (int bj = 0; bj < 2; ++bj)
; #pragma unroll
;                         for (int e = 0; e < 4; ++e) { r1[bj][e] = dpp_ror1(cur[bj][e]); r2[bj][e] = dpp_ror2(cur[bj][e]); }
; #pragma unroll
;                     for (int bj = 0; bj < 2; ++bj)
; #pragma unroll
;                         for (int e = 0; e < 4; ++e) { const float p1 = fr >= 1 ? r1[bj][e] : pr1[bj][e], p2 = fr >= 2 ? r2[bj][e] : pr2[bj][e];
;                             av[bj][e] = fma_s(w0[bj][e], p2, fma_s(w1[bj][e], p1, fma_s(w2[bj][e], cur[bj][e], bb[bj][e]))); }
;                     float o[4];
; #pragma unroll
;                     for (int e = 0; e < 4; ++e) o[e] = av[0][e] * sigmoid_f(av[0][e]) * av[1][e];
;                     const int lr = ai * HALF + wr * 64 + m * 16 + fr, t = t0 + lr;
;                     if (lr >= 2 && t < 4096) { u32x2 w; w.x = cvt_pk_bf16(o[0], o[1]); w.y = cvt_pk_bf16(o[2], o[3]);
;                         *(u32x2*)(gout + (size_t)(b * 4096 + t) * FF + j0 + n * 4) = w; }
.LBB0_894:
	s_or_b64 exec, exec, s[0:1]
	s_waitcnt lgkmcnt(0)
	s_barrier
	v_mov_b64_e32 v[160:161], 0
	v_mov_b64_e32 v[162:163], 0
	v_mov_b64_e32 v[168:169], 0
	v_mov_b64_e32 v[170:171], 0
	v_mov_b64_e32 v[164:165], 0
	v_mov_b64_e32 v[166:167], 0
	v_mov_b64_e32 v[172:173], 0
	v_mov_b64_e32 v[174:175], 0
	s_and_saveexec_b64 s[0:1], s[48:49]
	s_cbranch_execz .LBB0_896
	ds_read_b128 v[172:175], v218
	ds_read_b128 v[164:167], v218 offset:512
	ds_read_b128 v[168:171], v217 offset:1024
	ds_read_b128 v[160:163], v217 offset:1536
.LBB0_896:
	s_or_b64 exec, exec, s[0:1]
	v_fmamk_f32 v198, v244, 0x3a000000, v224
	v_mul_f32_e32 v199, 0x4b800000, v198
	v_cmp_gt_f32_e32 vcc, s35, v198
	s_or_b32 s0, s65, s92
	s_cmp_eq_u32 s0, 0
	v_cndmask_b32_e32 v198, v198, v199, vcc
	v_rsq_f32_e32 v198, v198
	s_cselect_b64 s[0:1], -1, 0
	s_and_b64 s[78:79], s[0:1], s[6:7]
	v_mul_f32_e32 v199, 0x45800000, v198
	v_cndmask_b32_e32 v204, v198, v199, vcc
	v_pk_mul_f32 v[100:101], v[100:101], v[204:205] op_sel_hi:[1,0]
	v_pk_mul_f32 v[96:97], v[96:97], v[204:205] op_sel_hi:[1,0]
	v_pk_mul_f32 v[98:99], v[98:99], v[204:205] op_sel_hi:[1,0]
	v_cndmask_b32_e64 v241, v96, 0, s[78:79]
	v_cndmask_b32_e64 v96, v100, 0, s[78:79]
	v_pk_mul_f32 v[102:103], v[102:103], v[204:205] op_sel_hi:[1,0]
	v_cndmask_b32_e64 v200, v98, 0, s[78:79]
	v_cndmask_b32_e64 v98, v101, 0, s[78:79]
	v_mov_b32_dpp v238, v96 row_ror:1 row_mask:0xf bank_mask:0xf
	v_cndmask_b32_e64 v102, v102, 0, s[78:79]
	v_mov_b32_dpp v239, v96 row_ror:2 row_mask:0xf bank_mask:0xf
	v_mov_b32_dpp v236, v98 row_ror:1 row_mask:0xf bank_mask:0xf
	s_waitcnt vmcnt(0) lgkmcnt(1)
	v_cndmask_b32_e64 v100, v238, v168, s[8:9]
	v_fma_f32 v96, v148, v96, v152
	v_cndmask_b32_e64 v242, v103, 0, s[78:79]
	v_mov_b32_dpp v237, v98 row_ror:2 row_mask:0xf bank_mask:0xf
	v_mov_b32_dpp v234, v102 row_ror:1 row_mask:0xf bank_mask:0xf
	v_cndmask_b32_e64 v168, v172, v239, s[10:11]
	v_fma_f32 v96, v144, v100, v96
	v_cndmask_b32_e64 v100, v236, v169, s[8:9]
	v_fma_f32 v98, v149, v98, v153
	v_mov_b32_dpp v235, v102 row_ror:2 row_mask:0xf bank_mask:0xf
	v_mov_b32_dpp v232, v242 row_ror:1 row_mask:0xf bank_mask:0xf
	v_fma_f32 v96, v136, v168, v96
	v_cndmask_b32_e64 v168, v173, v237, s[10:11]
	v_fma_f32 v98, v145, v100, v98
	v_cndmask_b32_e64 v100, v234, v170, s[8:9]
	v_fma_f32 v102, v150, v102, v154
	v_mov_b32_dpp v233, v242 row_ror:2 row_mask:0xf bank_mask:0xf
	v_fma_f32 v98, v137, v168, v98
	v_cndmask_b32_e64 v168, v174, v235, s[10:11]
	v_fma_f32 v100, v146, v100, v102
	v_cndmask_b32_e64 v102, v232, v171, s[8:9]
	v_mov_b32_dpp v230, v241 row_ror:1 row_mask:0xf bank_mask:0xf
	v_fma_f32 v100, v138, v168, v100
	v_cndmask_b32_e64 v168, v175, v233, s[10:11]
	v_fma_f32 v169, v151, v242, v155
	v_cndmask_b32_e64 v240, v97, 0, s[78:79]
	v_fma_f32 v102, v147, v102, v169
	v_mov_b32_dpp v231, v241 row_ror:2 row_mask:0xf bank_mask:0xf
	v_fma_f32 v168, v139, v168, v102
	s_waitcnt lgkmcnt(0)
	v_cndmask_b32_e64 v102, v230, v160, s[8:9]
	v_mov_b32_dpp v198, v240 row_ror:1 row_mask:0xf bank_mask:0xf
	v_cndmask_b32_e64 v160, v164, v231, s[10:11]
	v_fma_f32 v164, v128, v241, v132
	v_mov_b32_dpp v227, v240 row_ror:2 row_mask:0xf bank_mask:0xf
	v_fma_f32 v102, v124, v102, v164
	v_fma_f32 v102, v120, v160, v102
	v_cndmask_b32_e64 v160, v198, v161, s[8:9]
	v_mov_b32_dpp v101, v200 row_ror:1 row_mask:0xf bank_mask:0xf
	v_cndmask_b32_e64 v161, v165, v227, s[10:11]
	v_fma_f32 v164, v129, v240, v133
	v_cndmask_b32_e64 v199, v99, 0, s[78:79]
	v_fma_f32 v160, v125, v160, v164
	v_mov_b32_dpp v103, v200 row_ror:2 row_mask:0xf bank_mask:0xf
	v_fma_f32 v160, v121, v161, v160
	v_cndmask_b32_e64 v161, v101, v162, s[8:9]
	v_cndmask_b32_e64 v162, v166, v103, s[10:11]
	v_mov_b32_dpp v97, v199 row_ror:1 row_mask:0xf bank_mask:0xf
	v_fma_f32 v164, v130, v200, v134
	v_fma_f32 v161, v126, v161, v164
	v_cmp_gt_i32_e32 vcc, s68, v201
	v_fma_f32 v161, v122, v162, v161
	v_cndmask_b32_e64 v162, v97, v163, s[8:9]
	v_mov_b32_dpp v99, v199 row_ror:2 row_mask:0xf bank_mask:0xf
	v_fma_f32 v164, v131, v199, v135
	s_and_b64 s[80:81], s[46:47], vcc
	v_fma_f32 v162, v127, v162, v164
	v_add_u32_e32 v199, s59, v201
	v_cndmask_b32_e64 v163, v167, v99, s[10:11]
	v_fma_f32 v162, v123, v163, v162
	s_and_saveexec_b64 s[0:1], s[80:81]
	s_cbranch_execz .LBB0_898
	v_mul_f32_e32 v163, 0xbfb8aa3b, v168
	v_exp_f32_e32 v163, v163
	v_mul_f32_e32 v164, 0xbfb8aa3b, v100
	v_exp_f32_e32 v164, v164
	v_mul_f32_e32 v165, 0xbfb8aa3b, v98
	v_add_f32_e32 v163, 1.0, v163
	v_rcp_f32_e32 v163, v163
	v_add_f32_e32 v164, 1.0, v164
	v_exp_f32_e32 v165, v165
	v_rcp_f32_e32 v164, v164
	v_mul_f32_e32 v163, v168, v163
	v_mul_f32_e32 v162, v163, v162
	v_mul_f32_e32 v163, 0xbfb8aa3b, v96
	v_exp_f32_e32 v163, v163
	v_mul_f32_e32 v100, v100, v164
	v_add_f32_e32 v164, 1.0, v165
	v_rcp_f32_e32 v164, v164
	v_add_f32_e32 v163, 1.0, v163
	v_rcp_f32_e32 v163, v163
	v_mul_f32_e32 v100, v100, v161
	v_mul_f32_e32 v98, v98, v164
	v_mul_f32_e32 v98, v98, v160
	v_mul_f32_e32 v96, v96, v163
	v_mul_f32_e32 v96, v96, v102
	v_cvt_pk_bf16_f32 v160, v96, v98
	v_cvt_pk_bf16_f32 v161, v100, v162
	v_mul_u32_u24_e32 v162, s69, v199
	v_lshl_add_u32 v162, v192, 1, v162
	global_store_dwordx2 v162, v[160:161], s[36:37]
; __device__ __forceinline__ unsigned cvt_pk_bf16(float lo, float hi) { unsigned r; asm volatile("v_cvt_pk_bf16_f32 %0, %1, %2" : "=v"(r) : "v"(lo), "v"(hi)); return r; }
; __device__ __forceinline__ float sigmoid_f(float x) { return __builtin_amdgcn_rcpf(1.0f + __builtin_amdgcn_exp2f(-1.4426950408889634f * x)); }
; __device__ __forceinline__ float dpp_ror1(float v) { return __builtin_bit_cast(float, __builtin_amdgcn_update_dpp(0, __builtin_bit_cast(int, v), 0x121, 0xf, 0xf, false)); }
; __device__ __forceinline__ float dpp_ror2(float v) { return __builtin_bit_cast(float, __builtin_amdgcn_update_dpp(0, __builtin_bit_cast(int, v), 0x122, 0xf, 0xf, false)); }
; __device__ __forceinline__ float fma_s(float a, float b, float c) { float r; asm("v_fma_f32 %0, %1, %2, %3" : "=v"(r) : "v"(a), "v"(b), "v"(c)); return r; }
;     __device__ __forceinline__ void operator()(const f32x4 (&acc)[2][2][4][2], const Unit& u, int wr, int wc, int fr, int fq) const {
;     ...
;                 for (int m = 0; m < 4; ++m) {
;                     f32x4 cur[2] = {acc[ai][0][m][n] * r2v[ai][m], acc[ai][1][m][n] * r2v[ai][m]};
;                     if (first && ai == 0 && wr == 0 && m == 0 && fr < 2) { cur[0] = zero4; cur[1] = zero4; }
;                     f32x4 r1[2], r2[2], av[2];
; #pragma unroll
;                     for (int bj = 0; bj < 2; ++bj)
; #pragma unroll
;                         for (int e = 0; e < 4; ++e) { r1[bj][e] = dpp_ror1(cur[bj][e]); r2[bj][e] = dpp_ror2(cur[bj][e]); }
; #pragma unroll
;                     for (int bj = 0; bj < 2; ++bj)
; #pragma unroll
;                         for (int e = 0; e < 4; ++e) { const float p1 = fr >= 1 ? r1[bj][e] : pr1[bj][e], p2 = fr >= 2 ? r2[bj][e] : pr2[bj][e];
;                             av[bj][e] = fma_s(w0[bj][e], p2, fma_s(w1[bj][e], p1, fma_s(w2[bj][e], cur[bj][e], bb[bj][e]))); }
;                     float o[4];
; #pragma unroll
;                     for (int e = 0; e < 4; ++e) o[e] = av[0][e] * sigmoid_f(av[0][e]) * av[1][e];
;                     const int lr = ai * HALF + wr * 64 + m * 16 + fr, t = t0 + lr;
;                     if (lr >= 2 && t < 4096) { u32x2 w; w.x = cvt_pk_bf16(o[0], o[1]); w.y = cvt_pk_bf16(o[2], o[3]);
;                         *(u32x2*)(gout + (size_t)(b * 4096 + t) * FF + j0 + n * 4) = w; }
.LBB0_898:
	s_or_b64 exec, exec, s[0:1]
	v_fmamk_f32 v96, v245, 0x3a000000, v224
	v_mul_f32_e32 v98, 0x4b800000, v96
	v_cmp_gt_f32_e32 vcc, s35, v96
	s_nop 1
	v_cndmask_b32_e32 v96, v96, v98, vcc
	v_rsq_f32_e32 v96, v96
	s_nop 0
	v_mul_f32_e32 v98, 0x45800000, v96
	v_cndmask_b32_e32 v200, v96, v98, vcc
	v_pk_mul_f32 v[92:93], v[92:93], v[200:201] op_sel_hi:[1,0]
	v_pk_mul_f32 v[174:175], v[88:89], v[200:201] op_sel_hi:[1,0]
	v_pk_mul_f32 v[172:173], v[90:91], v[200:201] op_sel_hi:[1,0]
	v_mov_b32_dpp v170, v92 row_ror:1 row_mask:0xf bank_mask:0xf
	v_mov_b32_dpp v171, v92 row_ror:2 row_mask:0xf bank_mask:0xf
	v_cndmask_b32_e64 v88, v170, v238, s[8:9]
	v_mov_b32_dpp v168, v93 row_ror:1 row_mask:0xf bank_mask:0xf
	v_cndmask_b32_e64 v89, v239, v171, s[10:11]
	v_fma_f32 v90, v148, v92, v152
	v_pk_mul_f32 v[94:95], v[94:95], v[200:201] op_sel_hi:[1,0]
	v_fma_f32 v88, v144, v88, v90
	v_mov_b32_dpp v169, v93 row_ror:2 row_mask:0xf bank_mask:0xf
	v_fma_f32 v88, v136, v89, v88
	v_cndmask_b32_e64 v89, v168, v236, s[8:9]
	v_mov_b32_dpp v166, v94 row_ror:1 row_mask:0xf bank_mask:0xf
	v_cndmask_b32_e64 v90, v237, v169, s[10:11]
	v_fma_f32 v91, v149, v93, v153
	v_fma_f32 v89, v145, v89, v91
	v_mov_b32_dpp v167, v94 row_ror:2 row_mask:0xf bank_mask:0xf
	v_fma_f32 v89, v137, v90, v89
	v_cndmask_b32_e64 v90, v166, v234, s[8:9]
	v_mov_b32_dpp v163, v95 row_ror:1 row_mask:0xf bank_mask:0xf
	v_cndmask_b32_e64 v91, v235, v167, s[10:11]
	v_fma_f32 v92, v150, v94, v154
	v_fma_f32 v90, v146, v90, v92
	v_mov_b32_dpp v165, v95 row_ror:2 row_mask:0xf bank_mask:0xf
	v_fma_f32 v90, v138, v91, v90
	v_cndmask_b32_e64 v91, v163, v232, s[8:9]
	v_mov_b32_dpp v162, v174 row_ror:1 row_mask:0xf bank_mask:0xf
	v_cndmask_b32_e64 v92, v233, v165, s[10:11]
	v_fma_f32 v93, v151, v95, v155
	v_fma_f32 v91, v147, v91, v93
	v_mov_b32_dpp v164, v174 row_ror:2 row_mask:0xf bank_mask:0xf
	v_fma_f32 v92, v139, v92, v91
	v_cndmask_b32_e64 v91, v162, v230, s[8:9]
	v_mov_b32_dpp v160, v175 row_ror:1 row_mask:0xf bank_mask:0xf
	v_cndmask_b32_e64 v93, v231, v164, s[10:11]
	v_fma_f32 v94, v128, v174, v132
	v_fma_f32 v91, v124, v91, v94
	v_mov_b32_dpp v161, v175 row_ror:2 row_mask:0xf bank_mask:0xf
	v_fma_f32 v91, v120, v93, v91
	v_cndmask_b32_e64 v93, v160, v198, s[8:9]
	v_mov_b32_dpp v100, v172 row_ror:1 row_mask:0xf bank_mask:0xf
	v_cndmask_b32_e64 v94, v227, v161, s[10:11]
	v_fma_f32 v95, v129, v175, v133
	v_fma_f32 v93, v125, v93, v95
	v_mov_b32_dpp v102, v172 row_ror:2 row_mask:0xf bank_mask:0xf
	v_fma_f32 v93, v121, v94, v93
	v_cndmask_b32_e64 v94, v100, v101, s[8:9]
	v_mov_b32_dpp v96, v173 row_ror:1 row_mask:0xf bank_mask:0xf
	v_cndmask_b32_e64 v95, v103, v102, s[10:11]
	v_fma_f32 v101, v130, v172, v134
	s_nop 0
	v_fma_f32 v94, v126, v94, v101
	v_mov_b32_dpp v98, v173 row_ror:2 row_mask:0xf bank_mask:0xf
	v_fma_f32 v94, v122, v95, v94
	v_cndmask_b32_e64 v95, v96, v97, s[8:9]
	v_cndmask_b32_e64 v97, v99, v98, s[10:11]
	v_fma_f32 v99, v131, v173, v135
	s_nop 0
	v_fma_f32 v95, v127, v95, v99
	s_nop 0
	v_fma_f32 v95, v123, v97, v95
	v_add_u32_e32 v97, s71, v212
	v_cmp_gt_i32_e32 vcc, s68, v97
	s_and_b64 s[66:67], s[52:53], vcc
	v_add_u32_e32 v197, s59, v97
	s_and_saveexec_b64 s[0:1], s[66:67]
	s_cbranch_execz .LBB0_900
	v_mul_f32_e32 v97, 0xbfb8aa3b, v92
	v_exp_f32_e32 v97, v97
	v_mul_f32_e32 v99, 0xbfb8aa3b, v90
	v_mul_f32_e32 v101, 0xbfb8aa3b, v89
	v_exp_f32_e32 v99, v99
	v_add_f32_e32 v97, 1.0, v97
	v_rcp_f32_e32 v97, v97
	v_exp_f32_e32 v101, v101
	v_add_f32_e32 v99, 1.0, v99
	v_rcp_f32_e32 v99, v99
	v_mul_f32_e32 v92, v92, v97
	v_mul_f32_e32 v92, v92, v95
	v_mul_f32_e32 v95, 0xbfb8aa3b, v88
	v_exp_f32_e32 v95, v95
	v_add_f32_e32 v97, 1.0, v101
	v_rcp_f32_e32 v97, v97
	v_mul_f32_e32 v90, v90, v99
	v_add_f32_e32 v95, 1.0, v95
	v_rcp_f32_e32 v95, v95
	v_mul_f32_e32 v89, v89, v97
	v_mul_f32_e32 v90, v90, v94
	v_mul_f32_e32 v89, v89, v93
	v_mul_f32_e32 v88, v88, v95
	v_mul_f32_e32 v88, v88, v91
	v_cvt_pk_bf16_f32 v88, v88, v89
	v_cvt_pk_bf16_f32 v89, v90, v92
	v_mul_u32_u24_e32 v90, s69, v197
	v_lshl_add_u32 v90, v192, 1, v90
	global_store_dwordx2 v90, v[88:89], s[36:37]
.LBB0_900:
	s_or_b64 exec, exec, s[0:1]
	v_fmamk_f32 v88, v246, 0x3a000000, v224
	v_mul_f32_e32 v89, 0x4b800000, v88
	v_cmp_gt_f32_e32 vcc, s35, v88
	s_nop 1
	v_cndmask_b32_e32 v88, v88, v89, vcc
	v_rsq_f32_e32 v88, v88
	s_nop 0
	v_mul_f32_e32 v89, 0x45800000, v88
	v_cndmask_b32_e32 v198, v88, v89, vcc
	v_pk_mul_f32 v[174:175], v[84:85], v[198:199] op_sel_hi:[1,0]
	v_pk_mul_f32 v[172:173], v[86:87], v[198:199] op_sel_hi:[1,0]
	v_fma_f32 v101, v148, v174, v152
	v_fma_f32 v103, v149, v175, v153
	v_mov_b32_dpp v94, v174 row_ror:1 row_mask:0xf bank_mask:0xf
	v_mov_b32_dpp v95, v174 row_ror:2 row_mask:0xf bank_mask:0xf
	v_cndmask_b32_e64 v97, v94, v170, s[8:9]
	v_mov_b32_dpp v92, v175 row_ror:1 row_mask:0xf bank_mask:0xf
	v_cndmask_b32_e64 v99, v171, v95, s[10:11]
	v_fma_f32 v97, v144, v97, v101
	v_mov_b32_dpp v93, v175 row_ror:2 row_mask:0xf bank_mask:0xf
	v_fma_f32 v97, v136, v99, v97
	v_cndmask_b32_e64 v99, v92, v168, s[8:9]
	v_mov_b32_dpp v90, v172 row_ror:1 row_mask:0xf bank_mask:0xf
	v_cndmask_b32_e64 v101, v169, v93, s[10:11]
	v_fma_f32 v99, v145, v99, v103
	v_fma_f32 v101, v137, v101, v99
	v_cndmask_b32_e64 v99, v90, v166, s[8:9]
	v_mov_b32_dpp v91, v172 row_ror:2 row_mask:0xf bank_mask:0xf
	v_mov_b32_dpp v87, v173 row_ror:1 row_mask:0xf bank_mask:0xf
	v_fma_f32 v166, v150, v172, v154
	v_pk_mul_f32 v[232:233], v[80:81], v[198:199] op_sel_hi:[1,0]
	v_fma_f32 v99, v146, v99, v166
	v_cndmask_b32_e64 v103, v167, v91, s[10:11]
	v_fma_f32 v166, v138, v103, v99
	v_cndmask_b32_e64 v99, v87, v163, s[8:9]
; __device__ __forceinline__ unsigned cvt_pk_bf16(float lo, float hi) { unsigned r; asm volatile("v_cvt_pk_bf16_f32 %0, %1, %2" : "=v"(r) : "v"(lo), "v"(hi)); return r; }
; __device__ __forceinline__ float sigmoid_f(float x) { return __builtin_amdgcn_rcpf(1.0f + __builtin_amdgcn_exp2f(-1.4426950408889634f * x)); }
; __device__ __forceinline__ float dpp_ror1(float v) { return __builtin_bit_cast(float, __builtin_amdgcn_update_dpp(0, __builtin_bit_cast(int, v), 0x121, 0xf, 0xf, false)); }
; __device__ __forceinline__ float dpp_ror2(float v) { return __builtin_bit_cast(float, __builtin_amdgcn_update_dpp(0, __builtin_bit_cast(int, v), 0x122, 0xf, 0xf, false)); }
; __device__ __forceinline__ float fma_s(float a, float b, float c) { float r; asm("v_fma_f32 %0, %1, %2, %3" : "=v"(r) : "v"(a), "v"(b), "v"(c)); return r; }
;     __device__ __forceinline__ void operator()(const f32x4 (&acc)[2][2][4][2], const Unit& u, int wr, int wc, int fr, int fq) const {
;     ...
;                 for (int m = 0; m < 4; ++m) {
;                     f32x4 cur[2] = {acc[ai][0][m][n] * r2v[ai][m], acc[ai][1][m][n] * r2v[ai][m]};
;                     if (first && ai == 0 && wr == 0 && m == 0 && fr < 2) { cur[0] = zero4; cur[1] = zero4; }
;                     f32x4 r1[2], r2[2], av[2];
; #pragma unroll
;                     for (int bj = 0; bj < 2; ++bj)
; #pragma unroll
;                         for (int e = 0; e < 4; ++e) { r1[bj][e] = dpp_ror1(cur[bj][e]); r2[bj][e] = dpp_ror2(cur[bj][e]); }
; #pragma unroll
;                     for (int bj = 0; bj < 2; ++bj)
; #pragma unroll
;                         for (int e = 0; e < 4; ++e) { const float p1 = fr >= 1 ? r1[bj][e] : pr1[bj][e], p2 = fr >= 2 ? r2[bj][e] : pr2[bj][e];
;                             av[bj][e] = fma_s(w0[bj][e], p2, fma_s(w1[bj][e], p1, fma_s(w2[bj][e], cur[bj][e], bb[bj][e]))); }
;                     float o[4];
; #pragma unroll
;                     for (int e = 0; e < 4; ++e) o[e] = av[0][e] * sigmoid_f(av[0][e]) * av[1][e];
;                     const int lr = ai * HALF + wr * 64 + m * 16 + fr, t = t0 + lr;
;                     if (lr >= 2 && t < 4096) { u32x2 w; w.x = cvt_pk_bf16(o[0], o[1]); w.y = cvt_pk_bf16(o[2], o[3]);
;                         *(u32x2*)(gout + (size_t)(b * 4096 + t) * FF + j0 + n * 4) = w; }
	v_mov_b32_dpp v89, v173 row_ror:2 row_mask:0xf bank_mask:0xf
	v_mov_b32_dpp v86, v232 row_ror:1 row_mask:0xf bank_mask:0xf
	v_fma_f32 v163, v151, v173, v155
	v_fma_f32 v99, v147, v99, v163
	v_cndmask_b32_e64 v103, v165, v89, s[10:11]
	v_mov_b32_dpp v88, v232 row_ror:2 row_mask:0xf bank_mask:0xf
	v_fma_f32 v163, v139, v103, v99
	v_cndmask_b32_e64 v99, v86, v162, s[8:9]
	v_pk_mul_f32 v[230:231], v[82:83], v[198:199] op_sel_hi:[1,0]
	v_mov_b32_dpp v84, v233 row_ror:1 row_mask:0xf bank_mask:0xf
	v_cndmask_b32_e64 v103, v164, v88, s[10:11]
	v_fma_f32 v162, v128, v232, v132
	v_mov_b32_dpp v85, v233 row_ror:2 row_mask:0xf bank_mask:0xf
	v_fma_f32 v99, v124, v99, v162
	v_mov_b32_dpp v82, v230 row_ror:1 row_mask:0xf bank_mask:0xf
	v_fma_f32 v99, v120, v103, v99
	v_cndmask_b32_e64 v103, v84, v160, s[8:9]
	v_mov_b32_dpp v83, v230 row_ror:2 row_mask:0xf bank_mask:0xf
	v_mov_b32_dpp v80, v231 row_ror:1 row_mask:0xf bank_mask:0xf
	v_cndmask_b32_e64 v160, v161, v85, s[10:11]
	v_fma_f32 v161, v129, v233, v133
	v_cndmask_b32_e64 v100, v82, v100, s[8:9]
	v_fma_f32 v103, v125, v103, v161
	v_mov_b32_dpp v81, v231 row_ror:2 row_mask:0xf bank_mask:0xf
	v_fma_f32 v103, v121, v160, v103
	v_cndmask_b32_e64 v102, v102, v83, s[10:11]
	v_fma_f32 v160, v130, v230, v134
	v_cndmask_b32_e64 v96, v80, v96, s[8:9]
	v_fma_f32 v100, v126, v100, v160
	v_cndmask_b32_e64 v98, v98, v81, s[10:11]
	v_fma_f32 v100, v122, v102, v100
	v_fma_f32 v102, v131, v231, v135
	s_nop 0
	v_fma_f32 v96, v127, v96, v102
	s_nop 0
	v_fma_f32 v96, v123, v98, v96
	v_add_u32_e32 v98, s71, v213
	v_cmp_gt_i32_e32 vcc, s68, v98
	s_and_b64 s[0:1], s[52:53], vcc
	v_add_u32_e32 v195, s59, v98
	s_and_saveexec_b64 s[64:65], s[0:1]
	s_cbranch_execz .LBB0_902
	v_mul_f32_e32 v98, 0xbfb8aa3b, v163
	v_exp_f32_e32 v98, v98
	s_nop 0
	v_add_f32_e32 v98, 1.0, v98
	v_rcp_f32_e32 v98, v98
	s_nop 0
	v_mul_f32_e32 v98, v163, v98
	v_mul_f32_e32 v98, v98, v96
	v_mul_f32_e32 v96, 0xbfb8aa3b, v166
	v_exp_f32_e32 v96, v96
	s_nop 0
	v_add_f32_e32 v96, 1.0, v96
	v_rcp_f32_e32 v96, v96
	s_nop 0
	v_mul_f32_e32 v96, v166, v96
	v_mul_f32_e32 v100, v96, v100
	v_mul_f32_e32 v96, 0xbfb8aa3b, v101
	v_exp_f32_e32 v96, v96
	s_nop 0
	v_add_f32_e32 v96, 1.0, v96
	v_rcp_f32_e32 v96, v96
	s_nop 0
	v_mul_f32_e32 v96, v101, v96
	v_mul_f32_e32 v101, 0xbfb8aa3b, v97
	v_exp_f32_e32 v101, v101
	v_mul_f32_e32 v96, v96, v103
	v_add_f32_e32 v101, 1.0, v101
	v_rcp_f32_e32 v101, v101
	s_nop 0
	v_mul_f32_e32 v97, v97, v101
	v_mul_f32_e32 v97, v97, v99
	v_cvt_pk_bf16_f32 v96, v97, v96
	v_cvt_pk_bf16_f32 v97, v100, v98
	v_mul_u32_u24_e32 v98, s69, v195
	v_lshl_add_u32 v98, v192, 1, v98
	global_store_dwordx2 v98, v[96:97], s[36:37]
.LBB0_902:
	s_or_b64 exec, exec, s[64:65]
	v_pk_mul_f32 v[72:73], v[72:73], v[196:197] op_sel_hi:[1,0]
	v_pk_mul_f32 v[98:99], v[68:69], v[196:197] op_sel_hi:[1,0]
	v_pk_mul_f32 v[96:97], v[70:71], v[196:197] op_sel_hi:[1,0]
	v_mov_b32_dpp v68, v72 row_ror:1 row_mask:0xf bank_mask:0xf
	v_mov_b32_dpp v69, v72 row_ror:2 row_mask:0xf bank_mask:0xf
	v_cndmask_b32_e64 v68, v68, v94, s[8:9]
	v_mov_b32_dpp v70, v73 row_ror:1 row_mask:0xf bank_mask:0xf
	v_cndmask_b32_e64 v69, v95, v69, s[10:11]
	v_fma_f32 v72, v148, v72, v152
	v_pk_mul_f32 v[74:75], v[74:75], v[196:197] op_sel_hi:[1,0]
	v_fma_f32 v68, v144, v68, v72
	v_mov_b32_dpp v71, v73 row_ror:2 row_mask:0xf bank_mask:0xf
	v_fma_f32 v68, v136, v69, v68
	v_cndmask_b32_e64 v69, v70, v92, s[8:9]
	v_cndmask_b32_e64 v70, v93, v71, s[10:11]
	v_mov_b32_dpp v100, v74 row_ror:1 row_mask:0xf bank_mask:0xf
	v_fma_f32 v71, v149, v73, v153
	v_fma_f32 v69, v145, v69, v71
	v_fma_f32 v70, v137, v70, v69
	v_cndmask_b32_e64 v69, v100, v90, s[8:9]
	v_mov_b32_dpp v101, v74 row_ror:2 row_mask:0xf bank_mask:0xf
	v_mov_b32_dpp v102, v75 row_ror:1 row_mask:0xf bank_mask:0xf
	v_fma_f32 v72, v150, v74, v154
	v_fma_f32 v69, v146, v69, v72
	v_cndmask_b32_e64 v71, v91, v101, s[10:11]
	v_fma_f32 v72, v138, v71, v69
	v_cndmask_b32_e64 v69, v102, v87, s[8:9]
	v_mov_b32_dpp v103, v75 row_ror:2 row_mask:0xf bank_mask:0xf
	v_mov_b32_dpp v160, v98 row_ror:1 row_mask:0xf bank_mask:0xf
	v_fma_f32 v73, v151, v75, v155
	v_fma_f32 v69, v147, v69, v73
	v_cndmask_b32_e64 v71, v89, v103, s[10:11]
	v_mov_b32_dpp v161, v98 row_ror:2 row_mask:0xf bank_mask:0xf
	v_fma_f32 v73, v139, v71, v69
	v_cndmask_b32_e64 v69, v160, v86, s[8:9]
	v_mov_b32_dpp v162, v99 row_ror:1 row_mask:0xf bank_mask:0xf
	v_cndmask_b32_e64 v71, v88, v161, s[10:11]
	v_fma_f32 v74, v128, v98, v132
	v_fma_f32 v69, v124, v69, v74
	v_mov_b32_dpp v163, v99 row_ror:2 row_mask:0xf bank_mask:0xf
	v_fma_f32 v69, v120, v71, v69
	v_cndmask_b32_e64 v71, v162, v84, s[8:9]
	v_mov_b32_dpp v164, v96 row_ror:1 row_mask:0xf bank_mask:0xf
	v_cndmask_b32_e64 v74, v85, v163, s[10:11]
	v_fma_f32 v75, v129, v99, v133
	v_fma_f32 v71, v125, v71, v75
	v_mov_b32_dpp v165, v96 row_ror:2 row_mask:0xf bank_mask:0xf
	v_fma_f32 v71, v121, v74, v71
	v_cndmask_b32_e64 v74, v164, v82, s[8:9]
	v_mov_b32_dpp v166, v97 row_ror:1 row_mask:0xf bank_mask:0xf
	v_cndmask_b32_e64 v75, v83, v165, s[10:11]
	v_fma_f32 v82, v130, v96, v134
	s_nop 0
	v_fma_f32 v74, v126, v74, v82
	v_mov_b32_dpp v167, v97 row_ror:2 row_mask:0xf bank_mask:0xf
	v_fma_f32 v74, v122, v75, v74
	v_cndmask_b32_e64 v75, v166, v80, s[8:9]
	v_cndmask_b32_e64 v80, v81, v167, s[10:11]
	v_fma_f32 v81, v131, v97, v135
	s_nop 0
	v_fma_f32 v75, v127, v75, v81
	s_nop 0
	v_fma_f32 v75, v123, v80, v75
	v_add_u32_e32 v80, s71, v214
	v_cmp_gt_i32_e32 vcc, s68, v80
	s_and_b64 s[64:65], s[52:53], vcc
	v_add_u32_e32 v227, s59, v80
	s_and_saveexec_b64 s[76:77], s[64:65]
	s_cbranch_execz .LBB0_904
	v_mul_f32_e32 v80, 0xbfb8aa3b, v73
	v_exp_f32_e32 v80, v80
	s_nop 0
	v_add_f32_e32 v80, 1.0, v80
	v_rcp_f32_e32 v80, v80
	s_nop 0
	v_mul_f32_e32 v73, v73, v80
	v_mul_f32_e32 v73, v73, v75
	v_mul_f32_e32 v75, 0xbfb8aa3b, v72
	v_exp_f32_e32 v75, v75
	s_nop 0
	v_add_f32_e32 v75, 1.0, v75
	v_rcp_f32_e32 v75, v75
	s_nop 0
	v_mul_f32_e32 v72, v72, v75
	v_mul_f32_e32 v72, v72, v74
	v_mul_f32_e32 v74, 0xbfb8aa3b, v70
	v_exp_f32_e32 v74, v74
	s_nop 0
	v_add_f32_e32 v74, 1.0, v74
	v_rcp_f32_e32 v74, v74
	s_nop 0
	v_mul_f32_e32 v70, v70, v74
	v_mul_f32_e32 v70, v70, v71
	v_mul_f32_e32 v71, 0xbfb8aa3b, v68
	v_exp_f32_e32 v71, v71
	s_nop 0
	v_add_f32_e32 v71, 1.0, v71
	v_rcp_f32_e32 v71, v71
	s_nop 0
	v_mul_f32_e32 v68, v68, v71
	v_mul_f32_e32 v68, v68, v69
	v_cvt_pk_bf16_f32 v68, v68, v70
	v_mul_u32_u24_e32 v70, s69, v227
	v_lshl_add_u32 v70, v192, 1, v70
	v_cvt_pk_bf16_f32 v69, v72, v73
	global_store_dwordx2 v70, v[68:69], s[36:37]
;     __device__ __forceinline__ void operator()(const f32x4 (&acc)[2][2][4][2], const Unit& u, int wr, int wc, int fr, int fq) const {
;     ...
;             for (int ai = 0; ai < 2; ++ai) {
;                 f32x4 pr1[2] = {zero4, zero4}, pr2[2] = {zero4, zero4};
;                 const bool hasprev = (wr == 1) || (ai == 1);
;                 const int pg = (wr == 1) ? ai * 2 : (ai - 1) * 2 + 1;
;                 if (hasprev && fr < 2) {
; #pragma unroll
;                     for (int bj = 0; bj < 2; ++bj) {
;                         pr2[bj] = *(const PG8_LAS f32x4*)(xch + ((pg * 2 + fr) * 256 + bj * 128 + colx + n * 4));
;                         pr1[bj] = *(const PG8_LAS f32x4*)(xch + ((pg * 2 + 1) * 256 + bj * 128 + colx + n * 4)); }
;                 }
; #pragma unroll
;                 for (int m = 0; m < 4; ++m) {
;                     f32x4 cur[2] = {acc[ai][0][m][n] * r2v[ai][m], acc[ai][1][m][n] * r2v[ai][m]};
;                     if (first && ai == 0 && wr == 0 && m == 0 && fr < 2) { cur[0] = zero4; cur[1] = zero4; }
;                     f32x4 r1[2], r2[2], av[2];
; #pragma unroll
;                     for (int bj = 0; bj < 2; ++bj)
; #pragma unroll
;                         for (int e = 0; e < 4; ++e) { r1[bj][e] = dpp_ror1(cur[bj][e]); r2[bj][e] = dpp_ror2(cur[bj][e]); }
; #pragma unroll
;                     for (int bj = 0; bj < 2; ++bj)
; #pragma unroll
;                         for (int e = 0; e < 4; ++e) { const float p1 = fr >= 1 ? r1[bj][e] : pr1[bj][e], p2 = fr >= 2 ? r2[bj][e] : pr2[bj][e];
;                             av[bj][e] = fma_s(w0[bj][e], p2, fma_s(w1[bj][e], p1, fma_s(w2[bj][e], cur[bj][e], bb[bj][e]))); }
;                     float o[4];
; #pragma unroll
;                     for (int e = 0; e < 4; ++e) o[e] = av[0][e] * sigmoid_f(av[0][e]) * av[1][e];
;                     const int lr = ai * HALF + wr * 64 + m * 16 + fr, t = t0 + lr;
;                     if (lr >= 2 && t < 4096) { u32x2 w; w.x = cvt_pk_bf16(o[0], o[1]); w.y = cvt_pk_bf16(o[2], o[3]);
;                         *(u32x2*)(gout + (size_t)(b * 4096 + t) * FF + j0 + n * 4) = w; }
;                     pr1[0] = r1[0]; pr1[1] = r1[1]; pr2[0] = r2[0]; pr2[1] = r2[1];
;                 }
;                 if (n == 0 && ai == 0) {
; #pragma unroll
;                     for (int bj = 0; bj < 2; ++bj) { const int c = bj * FF + j0 + 4;
.LBB0_904:
	s_or_b64 exec, exec, s[76:77]
	v_or_b32_e32 v68, 4, v192
	v_ashrrev_i32_e32 v69, 31, v68
	v_lshlrev_b64 v[68:69], 2, v[68:69]
	v_lshl_add_u64 v[70:71], s[54:55], 0, v[68:69]
	v_lshl_add_u64 v[68:69], s[56:57], 0, v[68:69]
	global_load_dwordx4 v[88:91], v[202:203], off offset:16
	global_load_dwordx4 v[92:95], v[70:71], off
	global_load_dwordx4 v[96:99], v[68:69], off
	global_load_dwordx4 v[100:103], v[206:207], off offset:16
	v_add_u32_e32 v68, 0x1604, v192
	v_ashrrev_i32_e32 v69, 31, v68
	v_readlane_b32 s12, v254, 0
	v_lshlrev_b64 v[84:85], 2, v[68:69]
	v_readlane_b32 s14, v254, 2
	v_readlane_b32 s15, v254, 3
	v_readlane_b32 s16, v254, 4
	v_readlane_b32 s17, v254, 5
	v_lshl_add_u64 v[68:69], s[14:15], 0, v[84:85]
	v_lshl_add_u64 v[72:73], s[54:55], 0, v[84:85]
	v_lshl_add_u64 v[80:81], s[56:57], 0, v[84:85]
	v_lshl_add_u64 v[84:85], s[16:17], 0, v[84:85]
	global_load_dwordx4 v[68:71], v[68:69], off
	s_nop 0
	global_load_dwordx4 v[72:75], v[72:73], off
	v_mov_b32_e32 v160, 0
	global_load_dwordx4 v[80:83], v[80:81], off
	v_mov_b32_e32 v161, 0
	global_load_dwordx4 v[84:87], v[84:85], off
	v_mov_b64_e32 v[162:163], 0
	v_mov_b64_e32 v[168:169], 0
	v_mov_b64_e32 v[170:171], 0
	v_mov_b64_e32 v[164:165], 0
	v_mov_b64_e32 v[166:167], 0
	v_mov_b64_e32 v[172:173], 0
	v_mov_b64_e32 v[174:175], 0
	v_readlane_b32 s13, v254, 1
	v_readlane_b32 s18, v254, 6
	v_readlane_b32 s19, v254, 7
	s_and_saveexec_b64 s[76:77], s[6:7]
	s_cbranch_execz .LBB0_906
	ds_read_b128 v[172:175], v220
	ds_read_b128 v[164:167], v220 offset:512
	ds_read_b128 v[168:171], v219 offset:1024
	ds_read_b128 v[160:163], v219 offset:1536
.LBB0_906:
	s_or_b64 exec, exec, s[76:77]
	v_fmamk_f32 v202, v248, 0x3a000000, v224
	v_mul_f32_e32 v203, 0x4b800000, v202
	v_cmp_gt_f32_e32 vcc, s35, v202
	s_nop 1
	v_cndmask_b32_e32 v202, v202, v203, vcc
	v_rsq_f32_e32 v202, v202
	s_nop 0
	v_mul_f32_e32 v203, 0x45800000, v202
	v_cndmask_b32_e32 v202, v202, v203, vcc
	v_pk_mul_f32 v[238:239], v[156:157], v[202:203] op_sel_hi:[1,0]
	v_pk_mul_f32 v[242:243], v[140:141], v[202:203] op_sel_hi:[1,0]
	v_pk_mul_f32 v[236:237], v[158:159], v[202:203] op_sel_hi:[1,0]
	v_mov_b32_dpp v234, v238 row_ror:1 row_mask:0xf bank_mask:0xf
	v_mov_b32_dpp v235, v238 row_ror:2 row_mask:0xf bank_mask:0xf
	s_waitcnt lgkmcnt(1)
	v_cndmask_b32_e64 v140, v234, v168, s[8:9]
	v_mov_b32_dpp v232, v239 row_ror:1 row_mask:0xf bank_mask:0xf
	v_cndmask_b32_e64 v141, v172, v235, s[10:11]
	v_fma_f32 v168, v148, v238, v152
	v_mov_b32_dpp v233, v239 row_ror:2 row_mask:0xf bank_mask:0xf
	v_fma_f32 v140, v144, v140, v168
	v_mov_b32_dpp v230, v236 row_ror:1 row_mask:0xf bank_mask:0xf
	v_fma_f32 v140, v136, v141, v140
	v_cndmask_b32_e64 v141, v232, v169, s[8:9]
	v_cndmask_b32_e64 v168, v173, v233, s[10:11]
	v_fma_f32 v169, v149, v239, v153
	v_fma_f32 v141, v145, v141, v169
	v_mov_b32_dpp v231, v236 row_ror:2 row_mask:0xf bank_mask:0xf
	v_fma_f32 v168, v137, v168, v141
	v_cndmask_b32_e64 v141, v230, v170, s[8:9]
	v_mov_b32_dpp v206, v237 row_ror:1 row_mask:0xf bank_mask:0xf
	v_cndmask_b32_e64 v169, v174, v231, s[10:11]
	v_fma_f32 v170, v150, v236, v154
	v_pk_mul_f32 v[240:241], v[142:143], v[202:203] op_sel_hi:[1,0]
	v_fma_f32 v141, v146, v141, v170
	v_mov_b32_dpp v229, v237 row_ror:2 row_mask:0xf bank_mask:0xf
	v_fma_f32 v169, v138, v169, v141
	v_cndmask_b32_e64 v141, v206, v171, s[8:9]
	v_mov_b32_dpp v203, v242 row_ror:1 row_mask:0xf bank_mask:0xf
	v_cndmask_b32_e64 v170, v175, v229, s[10:11]
	v_fma_f32 v171, v151, v237, v155
	v_mov_b32_dpp v207, v242 row_ror:2 row_mask:0xf bank_mask:0xf
	v_fma_f32 v141, v147, v141, v171
	v_fma_f32 v170, v139, v170, v141
	s_waitcnt lgkmcnt(0)
	v_cndmask_b32_e64 v141, v203, v160, s[8:9]
	v_mov_b32_dpp v158, v243 row_ror:1 row_mask:0xf bank_mask:0xf
	v_cndmask_b32_e64 v160, v164, v207, s[10:11]
	v_fma_f32 v164, v128, v242, v132
	v_mov_b32_dpp v159, v243 row_ror:2 row_mask:0xf bank_mask:0xf
	v_fma_f32 v141, v124, v141, v164
	v_fma_f32 v160, v120, v160, v141
	v_cndmask_b32_e64 v141, v158, v161, s[8:9]
	v_mov_b32_dpp v156, v240 row_ror:1 row_mask:0xf bank_mask:0xf
	v_cndmask_b32_e64 v161, v165, v159, s[10:11]
	v_fma_f32 v164, v129, v243, v133
	v_mov_b32_dpp v157, v240 row_ror:2 row_mask:0xf bank_mask:0xf
	v_fma_f32 v141, v125, v141, v164
	v_fma_f32 v161, v121, v161, v141
	v_cndmask_b32_e64 v141, v156, v162, s[8:9]
	v_mov_b32_dpp v142, v241 row_ror:1 row_mask:0xf bank_mask:0xf
	v_cndmask_b32_e64 v162, v166, v157, s[10:11]
	v_fma_f32 v164, v130, v240, v134
	v_mov_b32_dpp v143, v241 row_ror:2 row_mask:0xf bank_mask:0xf
	v_fma_f32 v141, v126, v141, v164
	v_fma_f32 v164, v131, v241, v135
	s_nop 0
	v_fma_f32 v162, v122, v162, v141
	v_cndmask_b32_e64 v141, v142, v163, s[8:9]
	v_cndmask_b32_e64 v163, v167, v143, s[10:11]
	v_fma_f32 v141, v127, v141, v164
	s_nop 0
	v_fma_f32 v163, v123, v163, v141
	v_add_u32_e32 v141, 0x80, v201
	v_cmp_gt_i32_e32 vcc, s68, v141
	s_and_b64 s[76:77], s[4:5], vcc
	v_add_u32_e32 v141, s59, v141
	s_and_saveexec_b64 s[82:83], s[76:77]
	s_cbranch_execz .LBB0_908
	v_mul_f32_e32 v164, 0xbfb8aa3b, v170
	v_exp_f32_e32 v164, v164
	s_nop 0
	v_add_f32_e32 v164, 1.0, v164
	v_rcp_f32_e32 v164, v164
	s_nop 0
	v_mul_f32_e32 v164, v170, v164
	v_mul_f32_e32 v163, v164, v163
	v_mul_f32_e32 v164, 0xbfb8aa3b, v169
	v_exp_f32_e32 v164, v164
	s_nop 0
	v_add_f32_e32 v164, 1.0, v164
	v_rcp_f32_e32 v164, v164
	s_nop 0
	v_mul_f32_e32 v164, v169, v164
	v_mul_f32_e32 v162, v164, v162
	v_mul_f32_e32 v164, 0xbfb8aa3b, v168
	v_exp_f32_e32 v164, v164
	s_nop 0
	v_add_f32_e32 v164, 1.0, v164
	v_rcp_f32_e32 v164, v164
	s_nop 0
	v_mul_f32_e32 v164, v168, v164
	v_mul_f32_e32 v161, v164, v161
	v_mul_f32_e32 v164, 0xbfb8aa3b, v140
	v_exp_f32_e32 v164, v164
	s_nop 0
	v_add_f32_e32 v164, 1.0, v164
	v_rcp_f32_e32 v164, v164
	s_nop 0
	v_mul_f32_e32 v140, v140, v164
	v_mul_f32_e32 v140, v140, v160
	v_cvt_pk_bf16_f32 v160, v140, v161
	v_cvt_pk_bf16_f32 v161, v162, v163
	v_mul_u32_u24_e32 v162, s69, v141
	v_lshl_add_u32 v162, v192, 1, v162
	global_store_dwordx2 v162, v[160:161], s[36:37]
; __device__ __forceinline__ unsigned cvt_pk_bf16(float lo, float hi) { unsigned r; asm volatile("v_cvt_pk_bf16_f32 %0, %1, %2" : "=v"(r) : "v"(lo), "v"(hi)); return r; }
; __device__ __forceinline__ float sigmoid_f(float x) { return __builtin_amdgcn_rcpf(1.0f + __builtin_amdgcn_exp2f(-1.4426950408889634f * x)); }
; __device__ __forceinline__ float dpp_ror1(float v) { return __builtin_bit_cast(float, __builtin_amdgcn_update_dpp(0, __builtin_bit_cast(int, v), 0x121, 0xf, 0xf, false)); }
; __device__ __forceinline__ float dpp_ror2(float v) { return __builtin_bit_cast(float, __builtin_amdgcn_update_dpp(0, __builtin_bit_cast(int, v), 0x122, 0xf, 0xf, false)); }
; __device__ __forceinline__ float fma_s(float a, float b, float c) { float r; asm("v_fma_f32 %0, %1, %2, %3" : "=v"(r) : "v"(a), "v"(b), "v"(c)); return r; }
;     __device__ __forceinline__ void operator()(const f32x4 (&acc)[2][2][4][2], const Unit& u, int wr, int wc, int fr, int fq) const {
;     ...
;                 for (int m = 0; m < 4; ++m) {
;                     f32x4 cur[2] = {acc[ai][0][m][n] * r2v[ai][m], acc[ai][1][m][n] * r2v[ai][m]};
;                     if (first && ai == 0 && wr == 0 && m == 0 && fr < 2) { cur[0] = zero4; cur[1] = zero4; }
;                     f32x4 r1[2], r2[2], av[2];
; #pragma unroll
;                     for (int bj = 0; bj < 2; ++bj)
; #pragma unroll
;                         for (int e = 0; e < 4; ++e) { r1[bj][e] = dpp_ror1(cur[bj][e]); r2[bj][e] = dpp_ror2(cur[bj][e]); }
; #pragma unroll
;                     for (int bj = 0; bj < 2; ++bj)
; #pragma unroll
;                         for (int e = 0; e < 4; ++e) { const float p1 = fr >= 1 ? r1[bj][e] : pr1[bj][e], p2 = fr >= 2 ? r2[bj][e] : pr2[bj][e];
;                             av[bj][e] = fma_s(w0[bj][e], p2, fma_s(w1[bj][e], p1, fma_s(w2[bj][e], cur[bj][e], bb[bj][e]))); }
;                     float o[4];
; #pragma unroll
;                     for (int e = 0; e < 4; ++e) o[e] = av[0][e] * sigmoid_f(av[0][e]) * av[1][e];
;                     const int lr = ai * HALF + wr * 64 + m * 16 + fr, t = t0 + lr;
;                     if (lr >= 2 && t < 4096) { u32x2 w; w.x = cvt_pk_bf16(o[0], o[1]); w.y = cvt_pk_bf16(o[2], o[3]);
;                         *(u32x2*)(gout + (size_t)(b * 4096 + t) * FF + j0 + n * 4) = w; }
.LBB0_908:
	s_or_b64 exec, exec, s[82:83]
	v_fmamk_f32 v140, v249, 0x3a000000, v224
	v_mul_f32_e32 v160, 0x4b800000, v140
	v_cmp_gt_f32_e32 vcc, s35, v140
	s_nop 1
	v_cndmask_b32_e32 v140, v140, v160, vcc
	v_rsq_f32_e32 v140, v140
	s_nop 0
	v_mul_f32_e32 v160, 0x45800000, v140
	v_cndmask_b32_e32 v140, v140, v160, vcc
	v_pk_mul_f32 v[170:171], v[116:117], v[140:141] op_sel_hi:[1,0]
	v_pk_mul_f32 v[236:237], v[112:113], v[140:141] op_sel_hi:[1,0]
	v_pk_mul_f32 v[172:173], v[118:119], v[140:141] op_sel_hi:[1,0]
	v_mov_b32_dpp v168, v170 row_ror:1 row_mask:0xf bank_mask:0xf
	v_mov_b32_dpp v169, v170 row_ror:2 row_mask:0xf bank_mask:0xf
	v_cndmask_b32_e64 v112, v168, v234, s[8:9]
	v_mov_b32_dpp v166, v171 row_ror:1 row_mask:0xf bank_mask:0xf
	v_cndmask_b32_e64 v113, v235, v169, s[10:11]
	v_fma_f32 v170, v148, v170, v152
	v_mov_b32_dpp v167, v171 row_ror:2 row_mask:0xf bank_mask:0xf
	v_fma_f32 v112, v144, v112, v170
	v_mov_b32_dpp v164, v172 row_ror:1 row_mask:0xf bank_mask:0xf
	v_fma_f32 v112, v136, v113, v112
	v_cndmask_b32_e64 v113, v166, v232, s[8:9]
	v_fma_f32 v171, v149, v171, v153
	v_fma_f32 v113, v145, v113, v171
	v_cndmask_b32_e64 v170, v233, v167, s[10:11]
	v_fma_f32 v171, v137, v170, v113
	v_cndmask_b32_e64 v113, v164, v230, s[8:9]
	v_mov_b32_dpp v165, v172 row_ror:2 row_mask:0xf bank_mask:0xf
	v_mov_b32_dpp v161, v173 row_ror:1 row_mask:0xf bank_mask:0xf
	v_fma_f32 v172, v150, v172, v154
	v_fma_f32 v113, v146, v113, v172
	v_cndmask_b32_e64 v170, v231, v165, s[10:11]
	v_fma_f32 v172, v138, v170, v113
	v_cndmask_b32_e64 v113, v161, v206, s[8:9]
	v_mov_b32_dpp v163, v173 row_ror:2 row_mask:0xf bank_mask:0xf
	v_mov_b32_dpp v160, v236 row_ror:1 row_mask:0xf bank_mask:0xf
	v_fma_f32 v173, v151, v173, v155
	v_fma_f32 v113, v147, v113, v173
	v_cndmask_b32_e64 v170, v229, v163, s[10:11]
	v_mov_b32_dpp v162, v236 row_ror:2 row_mask:0xf bank_mask:0xf
	v_fma_f32 v173, v139, v170, v113
	v_cndmask_b32_e64 v113, v160, v203, s[8:9]
	v_mov_b32_dpp v118, v237 row_ror:1 row_mask:0xf bank_mask:0xf
	v_cndmask_b32_e64 v170, v207, v162, s[10:11]
	v_fma_f32 v203, v128, v236, v132
	v_pk_mul_f32 v[174:175], v[114:115], v[140:141] op_sel_hi:[1,0]
	v_fma_f32 v113, v124, v113, v203
	v_mov_b32_dpp v119, v237 row_ror:2 row_mask:0xf bank_mask:0xf
	v_fma_f32 v170, v120, v170, v113
	v_cndmask_b32_e64 v113, v118, v158, s[8:9]
	v_mov_b32_dpp v116, v174 row_ror:1 row_mask:0xf bank_mask:0xf
	v_cndmask_b32_e64 v158, v159, v119, s[10:11]
	v_fma_f32 v159, v129, v237, v133
	v_mov_b32_dpp v117, v174 row_ror:2 row_mask:0xf bank_mask:0xf
	v_fma_f32 v113, v125, v113, v159
	v_fma_f32 v158, v121, v158, v113
	v_cndmask_b32_e64 v113, v116, v156, s[8:9]
	v_mov_b32_dpp v114, v175 row_ror:1 row_mask:0xf bank_mask:0xf
	v_cndmask_b32_e64 v156, v157, v117, s[10:11]
	v_fma_f32 v157, v130, v174, v134
	v_mov_b32_dpp v115, v175 row_ror:2 row_mask:0xf bank_mask:0xf
	v_fma_f32 v113, v126, v113, v157
	v_readlane_b32 s12, v254, 22
	v_fma_f32 v156, v122, v156, v113
	v_cndmask_b32_e64 v113, v114, v142, s[8:9]
	v_cndmask_b32_e64 v142, v143, v115, s[10:11]
	v_fma_f32 v143, v131, v175, v135
	v_readlane_b32 s13, v254, 23
	v_fma_f32 v113, v127, v113, v143
	s_nop 0
	v_fma_f32 v142, v123, v142, v113
	v_add_u32_e32 v113, 0x90, v201
	v_cmp_gt_i32_e32 vcc, s68, v113
	s_and_b64 s[82:83], s[12:13], vcc
	v_add_u32_e32 v113, s59, v113
	s_and_saveexec_b64 s[84:85], s[82:83]
	s_cbranch_execz .LBB0_910
	v_mul_f32_e32 v143, 0xbfb8aa3b, v173
	v_exp_f32_e32 v143, v143
	v_mul_f32_e32 v157, 0xbfb8aa3b, v112
	v_exp_f32_e32 v157, v157
	v_add_f32_e32 v143, 1.0, v143
	v_rcp_f32_e32 v143, v143
	v_add_f32_e32 v157, 1.0, v157
	v_rcp_f32_e32 v157, v157
	v_mul_f32_e32 v143, v173, v143
	v_mul_f32_e32 v143, v143, v142
	v_mul_f32_e32 v142, 0xbfb8aa3b, v172
	v_exp_f32_e32 v142, v142
	v_mul_f32_e32 v112, v112, v157
	v_mul_f32_e32 v112, v112, v170
	v_add_f32_e32 v142, 1.0, v142
	v_rcp_f32_e32 v142, v142
	s_nop 0
	v_mul_f32_e32 v142, v172, v142
	v_mul_f32_e32 v156, v142, v156
	v_mul_f32_e32 v142, 0xbfb8aa3b, v171
	v_exp_f32_e32 v142, v142
	s_nop 0
	v_add_f32_e32 v142, 1.0, v142
	v_rcp_f32_e32 v142, v142
	s_nop 0
	v_mul_f32_e32 v142, v171, v142
	v_mul_f32_e32 v142, v142, v158
	v_cvt_pk_bf16_f32 v142, v112, v142
	v_cvt_pk_bf16_f32 v143, v156, v143
	v_mul_u32_u24_e32 v156, s69, v113
	v_lshl_add_u32 v156, v192, 1, v156
	global_store_dwordx2 v156, v[142:143], s[36:37]

; __device__ __forceinline__ unsigned cvt_pk_bf16(float lo, float hi) { unsigned r; asm volatile("v_cvt_pk_bf16_f32 %0, %1, %2" : "=v"(r) : "v"(lo), "v"(hi)); return r; }
; __device__ __forceinline__ float sigmoid_f(float x) { return __builtin_amdgcn_rcpf(1.0f + __builtin_amdgcn_exp2f(-1.4426950408889634f * x)); }
; __device__ __forceinline__ float dpp_ror1(float v) { return __builtin_bit_cast(float, __builtin_amdgcn_update_dpp(0, __builtin_bit_cast(int, v), 0x121, 0xf, 0xf, false)); }
; __device__ __forceinline__ float dpp_ror2(float v) { return __builtin_bit_cast(float, __builtin_amdgcn_update_dpp(0, __builtin_bit_cast(int, v), 0x122, 0xf, 0xf, false)); }
; __device__ __forceinline__ float fma_s(float a, float b, float c) { float r; asm("v_fma_f32 %0, %1, %2, %3" : "=v"(r) : "v"(a), "v"(b), "v"(c)); return r; }
;     __device__ __forceinline__ void operator()(const f32x4 (&acc)[2][2][4][2], const Unit& u, int wr, int wc, int fr, int fq) const {
;     ...
;                 for (int m = 0; m < 4; ++m) {
;                     f32x4 cur[2] = {acc[ai][0][m][n] * r2v[ai][m], acc[ai][1][m][n] * r2v[ai][m]};
;                     if (first && ai == 0 && wr == 0 && m == 0 && fr < 2) { cur[0] = zero4; cur[1] = zero4; }
;                     f32x4 r1[2], r2[2], av[2];
; #pragma unroll
;                     for (int bj = 0; bj < 2; ++bj)
; #pragma unroll
;                         for (int e = 0; e < 4; ++e) { r1[bj][e] = dpp_ror1(cur[bj][e]); r2[bj][e] = dpp_ror2(cur[bj][e]); }
; #pragma unroll
;                     for (int bj = 0; bj < 2; ++bj)
; #pragma unroll
;                         for (int e = 0; e < 4; ++e) { const float p1 = fr >= 1 ? r1[bj][e] : pr1[bj][e], p2 = fr >= 2 ? r2[bj][e] : pr2[bj][e];
;                             av[bj][e] = fma_s(w0[bj][e], p2, fma_s(w1[bj][e], p1, fma_s(w2[bj][e], cur[bj][e], bb[bj][e]))); }
;                     float o[4];
; #pragma unroll
;                     for (int e = 0; e < 4; ++e) o[e] = av[0][e] * sigmoid_f(av[0][e]) * av[1][e];
;                     const int lr = ai * HALF + wr * 64 + m * 16 + fr, t = t0 + lr;
;                     if (lr >= 2 && t < 4096) { u32x2 w; w.x = cvt_pk_bf16(o[0], o[1]); w.y = cvt_pk_bf16(o[2], o[3]);
;                         *(u32x2*)(gout + (size_t)(b * 4096 + t) * FF + j0 + n * 4) = w; }
.Lp9pre_skip:
	v_mul_f32_e32 v142, 0x4b800000, v112
	v_cmp_gt_f32_e32 vcc, s35, v112
	s_nop 1
	v_cndmask_b32_e32 v112, v112, v142, vcc
	v_rsq_f32_e32 v112, v112
	s_nop 0
	v_mul_f32_e32 v142, 0x45800000, v112
	v_cndmask_b32_e32 v112, v112, v142, vcc
	v_pk_mul_f32 v[174:175], v[108:109], v[112:113] op_sel_hi:[1,0]
	v_pk_mul_f32 v[172:173], v[110:111], v[112:113] op_sel_hi:[1,0]
	s_nop 0
	v_mov_b32_dpp v170, v174 row_ror:1 row_mask:0xf bank_mask:0xf
	v_mov_b32_dpp v171, v174 row_ror:2 row_mask:0xf bank_mask:0xf
	v_mov_b32_dpp v158, v175 row_ror:1 row_mask:0xf bank_mask:0xf
	v_cndmask_b32_e64 v168, v170, v168, s[8:9]
	v_mov_b32_dpp v159, v175 row_ror:2 row_mask:0xf bank_mask:0xf
	v_mov_b32_dpp v156, v172 row_ror:1 row_mask:0xf bank_mask:0xf
	v_cndmask_b32_e64 v169, v169, v171, s[10:11]
	v_fma_f32 v174, v148, v174, v152
	v_cndmask_b32_e64 v166, v158, v166, s[8:9]
	v_fma_f32 v168, v144, v168, v174
	v_pk_mul_f32 v[228:229], v[104:105], v[112:113] op_sel_hi:[1,0]
	v_mov_b32_dpp v157, v172 row_ror:2 row_mask:0xf bank_mask:0xf
	v_mov_b32_dpp v111, v173 row_ror:1 row_mask:0xf bank_mask:0xf
	v_fma_f32 v168, v136, v169, v168
	v_cndmask_b32_e64 v167, v167, v159, s[10:11]
	v_fma_f32 v169, v149, v175, v153
	v_cndmask_b32_e64 v164, v156, v164, s[8:9]
	v_fma_f32 v166, v145, v166, v169
	v_mov_b32_dpp v143, v173 row_ror:2 row_mask:0xf bank_mask:0xf
	v_mov_b32_dpp v110, v228 row_ror:1 row_mask:0xf bank_mask:0xf
	v_fma_f32 v166, v137, v167, v166
	v_cndmask_b32_e64 v165, v165, v157, s[10:11]
	v_fma_f32 v167, v150, v172, v154
	v_cndmask_b32_e64 v161, v111, v161, s[8:9]
	v_fma_f32 v164, v146, v164, v167
	v_pk_mul_f32 v[206:207], v[106:107], v[112:113] op_sel_hi:[1,0]
	v_mov_b32_dpp v142, v228 row_ror:2 row_mask:0xf bank_mask:0xf
	v_mov_b32_dpp v108, v229 row_ror:1 row_mask:0xf bank_mask:0xf
	v_fma_f32 v164, v138, v165, v164
	v_cndmask_b32_e64 v163, v163, v143, s[10:11]
	v_fma_f32 v165, v151, v173, v155
	v_cndmask_b32_e64 v160, v110, v160, s[8:9]
	v_fma_f32 v161, v147, v161, v165
	v_mov_b32_dpp v109, v229 row_ror:2 row_mask:0xf bank_mask:0xf
	v_mov_b32_dpp v106, v206 row_ror:1 row_mask:0xf bank_mask:0xf
	v_fma_f32 v161, v139, v163, v161
	v_cndmask_b32_e64 v162, v162, v142, s[10:11]
	v_fma_f32 v163, v128, v228, v132
	v_cndmask_b32_e64 v118, v108, v118, s[8:9]
	v_fma_f32 v160, v124, v160, v163
	v_mov_b32_dpp v107, v206 row_ror:2 row_mask:0xf bank_mask:0xf
	v_mov_b32_dpp v104, v207 row_ror:1 row_mask:0xf bank_mask:0xf
	v_fma_f32 v160, v120, v162, v160
	v_cndmask_b32_e64 v119, v119, v109, s[10:11]
	v_fma_f32 v162, v129, v229, v133
	v_cndmask_b32_e64 v116, v106, v116, s[8:9]
	v_fma_f32 v118, v125, v118, v162
	v_mov_b32_dpp v105, v207 row_ror:2 row_mask:0xf bank_mask:0xf
	v_fma_f32 v118, v121, v119, v118
	v_cndmask_b32_e64 v117, v117, v107, s[10:11]
	v_fma_f32 v119, v130, v206, v134
	v_cndmask_b32_e64 v114, v104, v114, s[8:9]
	v_fma_f32 v116, v126, v116, v119
	v_cndmask_b32_e64 v115, v115, v105, s[10:11]
	v_fma_f32 v116, v122, v117, v116
	v_fma_f32 v117, v131, v207, v135
	v_readlane_b32 s12, v254, 24
	v_fma_f32 v114, v127, v114, v117
	v_readlane_b32 s13, v254, 25
	v_fma_f32 v115, v123, v115, v114
	v_add_u32_e32 v114, 0xa0, v201
	v_cmp_gt_i32_e32 vcc, s68, v114
	s_and_b64 s[84:85], s[12:13], vcc
	v_add_u32_e32 v114, s59, v114
	s_and_saveexec_b64 s[86:87], s[84:85]
	s_cbranch_execz .LBB0_912
	v_mul_f32_e32 v117, 0xbfb8aa3b, v161
	v_exp_f32_e32 v117, v117
	s_nop 0
	v_add_f32_e32 v117, 1.0, v117
	v_rcp_f32_e32 v117, v117
	s_nop 0
	v_mul_f32_e32 v117, v161, v117
	v_mul_f32_e32 v115, v117, v115
	v_mul_f32_e32 v117, 0xbfb8aa3b, v164
	v_exp_f32_e32 v117, v117
	s_nop 0
	v_add_f32_e32 v117, 1.0, v117
	v_rcp_f32_e32 v117, v117
	s_nop 0
	v_mul_f32_e32 v117, v164, v117
	v_mul_f32_e32 v117, v117, v116
	v_mul_f32_e32 v116, 0xbfb8aa3b, v166
	v_exp_f32_e32 v116, v116
	s_nop 0
	v_add_f32_e32 v116, 1.0, v116
	v_rcp_f32_e32 v116, v116
	s_nop 0
	v_mul_f32_e32 v116, v166, v116
	v_mul_f32_e32 v116, v116, v118
	v_mul_f32_e32 v118, 0xbfb8aa3b, v168
	v_exp_f32_e32 v118, v118
	s_nop 0
	v_add_f32_e32 v118, 1.0, v118
	v_rcp_f32_e32 v118, v118
	s_nop 0
	v_mul_f32_e32 v118, v168, v118
	v_mul_f32_e32 v118, v118, v160
	v_cvt_pk_bf16_f32 v116, v118, v116
	v_mul_u32_u24_e32 v118, s69, v114
	v_lshl_add_u32 v118, v192, 1, v118
	v_cvt_pk_bf16_f32 v117, v117, v115
	global_store_dwordx2 v118, v[116:117], s[36:37]
; #define PG8_LAS __attribute__((address_space(3)))
; __device__ __forceinline__ unsigned cvt_pk_bf16(float lo, float hi) { unsigned r; asm volatile("v_cvt_pk_bf16_f32 %0, %1, %2" : "=v"(r) : "v"(lo), "v"(hi)); return r; }
;     __device__ __forceinline__ void operator()(const f32x4 (&acc)[2][2][4][2], const Unit& u, int wr, int wc, int fr, int fq) const {
;     ...
;                 f32x4 pr1[2] = {zero4, zero4}, pr2[2] = {zero4, zero4};
;                 const bool hasprev = (wr == 1) || (ai == 1);
;                 const int pg = (wr == 1) ? ai * 2 : (ai - 1) * 2 + 1;
;                 if (hasprev && fr < 2) {
; #pragma unroll
;                     for (int bj = 0; bj < 2; ++bj) {
;                         pr2[bj] = *(const PG8_LAS f32x4*)(xch + ((pg * 2 + fr) * 256 + bj * 128 + colx + n * 4));
;                         pr1[bj] = *(const PG8_LAS f32x4*)(xch + ((pg * 2 + 1) * 256 + bj * 128 + colx + n * 4)); }
;                 }
; #pragma unroll
;                 for (int m = 0; m < 4; ++m) {
;                     f32x4 cur[2] = {acc[ai][0][m][n] * r2v[ai][m], acc[ai][1][m][n] * r2v[ai][m]};
;                     if (first && ai == 0 && wr == 0 && m == 0 && fr < 2) { cur[0] = zero4; cur[1] = zero4; }
;                     f32x4 r1[2], r2[2], av[2];
; #pragma unroll
;                     for (int bj = 0; bj < 2; ++bj)
; #pragma unroll
;                         for (int e = 0; e < 4; ++e) { r1[bj][e] = dpp_ror1(cur[bj][e]); r2[bj][e] = dpp_ror2(cur[bj][e]); }
; #pragma unroll
;                     for (int bj = 0; bj < 2; ++bj)
; #pragma unroll
;                         for (int e = 0; e < 4; ++e) { const float p1 = fr >= 1 ? r1[bj][e] : pr1[bj][e], p2 = fr >= 2 ? r2[bj][e] : pr2[bj][e];
;                             av[bj][e] = fma_s(w0[bj][e], p2, fma_s(w1[bj][e], p1, fma_s(w2[bj][e], cur[bj][e], bb[bj][e]))); }
;                     float o[4];
; #pragma unroll
;                     for (int e = 0; e < 4; ++e) o[e] = av[0][e] * sigmoid_f(av[0][e]) * av[1][e];
;                     const int lr = ai * HALF + wr * 64 + m * 16 + fr, t = t0 + lr;
;                     if (lr >= 2 && t < 4096) { u32x2 w; w.x = cvt_pk_bf16(o[0], o[1]); w.y = cvt_pk_bf16(o[2], o[3]);
;                         *(u32x2*)(gout + (size_t)(b * 4096 + t) * FF + j0 + n * 4) = w; }
;                     pr1[0] = r1[0]; pr1[1] = r1[1]; pr2[0] = r2[0]; pr2[1] = r2[1];
;                 }
.LBB0_912:
	s_or_b64 exec, exec, s[86:87]
	v_pk_mul_f32 v[76:77], v[76:77], v[194:195] op_sel_hi:[1,0]
	v_pk_mul_f32 v[118:119], v[64:65], v[194:195] op_sel_hi:[1,0]
	v_pk_mul_f32 v[116:117], v[66:67], v[194:195] op_sel_hi:[1,0]
	v_mov_b32_dpp v64, v76 row_ror:1 row_mask:0xf bank_mask:0xf
	v_mov_b32_dpp v65, v76 row_ror:2 row_mask:0xf bank_mask:0xf
	v_cndmask_b32_e64 v64, v64, v170, s[8:9]
	v_mov_b32_dpp v66, v77 row_ror:1 row_mask:0xf bank_mask:0xf
	v_cndmask_b32_e64 v65, v171, v65, s[10:11]
	v_fma_f32 v76, v148, v76, v152
	v_pk_mul_f32 v[78:79], v[78:79], v[194:195] op_sel_hi:[1,0]
	v_fma_f32 v64, v144, v64, v76
	v_mov_b32_dpp v67, v77 row_ror:2 row_mask:0xf bank_mask:0xf
	v_fma_f32 v64, v136, v65, v64
	v_cndmask_b32_e64 v65, v66, v158, s[8:9]
	v_cndmask_b32_e64 v66, v159, v67, s[10:11]
	v_mov_b32_dpp v115, v78 row_ror:1 row_mask:0xf bank_mask:0xf
	v_fma_f32 v67, v149, v77, v153
	v_fma_f32 v65, v145, v65, v67
	v_fma_f32 v66, v137, v66, v65
	v_cndmask_b32_e64 v65, v115, v156, s[8:9]
	v_mov_b32_dpp v160, v78 row_ror:2 row_mask:0xf bank_mask:0xf
	v_mov_b32_dpp v161, v79 row_ror:1 row_mask:0xf bank_mask:0xf
	v_fma_f32 v76, v150, v78, v154
	v_fma_f32 v65, v146, v65, v76
	v_cndmask_b32_e64 v67, v157, v160, s[10:11]
	v_fma_f32 v76, v138, v67, v65
	v_cndmask_b32_e64 v65, v161, v111, s[8:9]
	v_mov_b32_dpp v162, v79 row_ror:2 row_mask:0xf bank_mask:0xf
	v_mov_b32_dpp v163, v118 row_ror:1 row_mask:0xf bank_mask:0xf
	v_fma_f32 v77, v151, v79, v155
	v_fma_f32 v65, v147, v65, v77
	v_cndmask_b32_e64 v67, v143, v162, s[10:11]
	v_mov_b32_dpp v164, v118 row_ror:2 row_mask:0xf bank_mask:0xf
	v_fma_f32 v77, v139, v67, v65
	v_cndmask_b32_e64 v65, v163, v110, s[8:9]
	v_mov_b32_dpp v165, v119 row_ror:1 row_mask:0xf bank_mask:0xf
	v_cndmask_b32_e64 v67, v142, v164, s[10:11]
	v_fma_f32 v78, v128, v118, v132
	v_fma_f32 v65, v124, v65, v78
	v_mov_b32_dpp v166, v119 row_ror:2 row_mask:0xf bank_mask:0xf
	v_fma_f32 v65, v120, v67, v65
	v_cndmask_b32_e64 v67, v165, v108, s[8:9]
	v_mov_b32_dpp v167, v116 row_ror:1 row_mask:0xf bank_mask:0xf
	v_cndmask_b32_e64 v78, v109, v166, s[10:11]
	v_fma_f32 v79, v129, v119, v133
	v_fma_f32 v67, v125, v67, v79
	v_mov_b32_dpp v168, v116 row_ror:2 row_mask:0xf bank_mask:0xf
	v_fma_f32 v67, v121, v78, v67
	v_cndmask_b32_e64 v78, v167, v106, s[8:9]
	v_mov_b32_dpp v169, v117 row_ror:1 row_mask:0xf bank_mask:0xf
	v_cndmask_b32_e64 v79, v107, v168, s[10:11]
	v_fma_f32 v106, v130, v116, v134
	s_nop 0
	v_fma_f32 v78, v126, v78, v106
	v_mov_b32_dpp v172, v117 row_ror:2 row_mask:0xf bank_mask:0xf
	v_fma_f32 v78, v122, v79, v78
	v_cndmask_b32_e64 v79, v169, v104, s[8:9]
	v_cndmask_b32_e64 v104, v105, v172, s[10:11]
	v_fma_f32 v105, v131, v117, v135
	s_nop 0
	v_fma_f32 v79, v127, v79, v105
	s_nop 0
	v_fma_f32 v79, v123, v104, v79
	v_add_u32_e32 v104, 0xb0, v201
	v_cmp_gt_i32_e32 vcc, s68, v104
	s_and_b64 s[86:87], s[20:21], vcc
	v_add_u32_e32 v115, s59, v104
	s_and_saveexec_b64 s[88:89], s[86:87]
	s_cbranch_execz .LBB0_914
	v_mul_f32_e32 v104, 0xbfb8aa3b, v77
	v_exp_f32_e32 v104, v104
	s_nop 0
	v_add_f32_e32 v104, 1.0, v104
	v_rcp_f32_e32 v104, v104
	s_nop 0
	v_mul_f32_e32 v77, v77, v104
	v_mul_f32_e32 v77, v77, v79
	v_mul_f32_e32 v79, 0xbfb8aa3b, v76
	v_exp_f32_e32 v79, v79
	s_nop 0
	v_add_f32_e32 v79, 1.0, v79
	v_rcp_f32_e32 v79, v79
	s_nop 0
	v_mul_f32_e32 v76, v76, v79
	v_mul_f32_e32 v76, v76, v78
	v_mul_f32_e32 v78, 0xbfb8aa3b, v66
	v_exp_f32_e32 v78, v78
	s_nop 0
	v_add_f32_e32 v78, 1.0, v78
	v_rcp_f32_e32 v78, v78
	s_nop 0
	v_mul_f32_e32 v66, v66, v78
	v_mul_f32_e32 v66, v66, v67
	v_mul_f32_e32 v67, 0xbfb8aa3b, v64
	v_exp_f32_e32 v67, v67
	s_nop 0
	v_add_f32_e32 v67, 1.0, v67
	v_rcp_f32_e32 v67, v67
	s_nop 0
	v_mul_f32_e32 v64, v64, v67
	v_mul_f32_e32 v64, v64, v65
	v_cvt_pk_bf16_f32 v64, v64, v66
	v_mul_u32_u24_e32 v66, s69, v115
	v_lshl_add_u32 v66, v192, 1, v66
	v_cvt_pk_bf16_f32 v65, v76, v77
	global_store_dwordx2 v66, v[64:65], s[36:37]
.LBB0_914:
	s_or_b64 exec, exec, s[88:89]
	v_mov_b64_e32 v[64:65], 0
	v_mov_b64_e32 v[66:67], 0
	v_mov_b64_e32 v[104:105], 0
	v_mov_b64_e32 v[106:107], 0
	v_mov_b64_e32 v[76:77], 0
	v_mov_b64_e32 v[78:79], 0
	v_mov_b64_e32 v[108:109], 0
	v_mov_b64_e32 v[110:111], 0
	s_and_saveexec_b64 s[88:89], s[48:49]
	s_cbranch_execz .LBB0_916
	ds_read_b128 v[108:111], v218 offset:16
	ds_read_b128 v[76:79], v218 offset:528
	ds_read_b128 v[104:107], v217 offset:1040
	ds_read_b128 v[64:67], v217 offset:1552
; __device__ __forceinline__ unsigned cvt_pk_bf16(float lo, float hi) { unsigned r; asm volatile("v_cvt_pk_bf16_f32 %0, %1, %2" : "=v"(r) : "v"(lo), "v"(hi)); return r; }
; __device__ __forceinline__ float sigmoid_f(float x) { return __builtin_amdgcn_rcpf(1.0f + __builtin_amdgcn_exp2f(-1.4426950408889634f * x)); }
; __device__ __forceinline__ float dpp_ror1(float v) { return __builtin_bit_cast(float, __builtin_amdgcn_update_dpp(0, __builtin_bit_cast(int, v), 0x121, 0xf, 0xf, false)); }
; __device__ __forceinline__ float dpp_ror2(float v) { return __builtin_bit_cast(float, __builtin_amdgcn_update_dpp(0, __builtin_bit_cast(int, v), 0x122, 0xf, 0xf, false)); }
; __device__ __forceinline__ float fma_s(float a, float b, float c) { float r; asm("v_fma_f32 %0, %1, %2, %3" : "=v"(r) : "v"(a), "v"(b), "v"(c)); return r; }
;     __device__ __forceinline__ void operator()(const f32x4 (&acc)[2][2][4][2], const Unit& u, int wr, int wc, int fr, int fq) const {
;     ...
;                 for (int m = 0; m < 4; ++m) {
;                     f32x4 cur[2] = {acc[ai][0][m][n] * r2v[ai][m], acc[ai][1][m][n] * r2v[ai][m]};
;                     if (first && ai == 0 && wr == 0 && m == 0 && fr < 2) { cur[0] = zero4; cur[1] = zero4; }
;                     f32x4 r1[2], r2[2], av[2];
; #pragma unroll
;                     for (int bj = 0; bj < 2; ++bj)
; #pragma unroll
;                         for (int e = 0; e < 4; ++e) { r1[bj][e] = dpp_ror1(cur[bj][e]); r2[bj][e] = dpp_ror2(cur[bj][e]); }
; #pragma unroll
;                     for (int bj = 0; bj < 2; ++bj)
; #pragma unroll
;                         for (int e = 0; e < 4; ++e) { const float p1 = fr >= 1 ? r1[bj][e] : pr1[bj][e], p2 = fr >= 2 ? r2[bj][e] : pr2[bj][e];
;                             av[bj][e] = fma_s(w0[bj][e], p2, fma_s(w1[bj][e], p1, fma_s(w2[bj][e], cur[bj][e], bb[bj][e]))); }
;                     float o[4];
; #pragma unroll
;                     for (int e = 0; e < 4; ++e) o[e] = av[0][e] * sigmoid_f(av[0][e]) * av[1][e];
;                     const int lr = ai * HALF + wr * 64 + m * 16 + fr, t = t0 + lr;
;                     if (lr >= 2 && t < 4096) { u32x2 w; w.x = cvt_pk_bf16(o[0], o[1]); w.y = cvt_pk_bf16(o[2], o[3]);
;                         *(u32x2*)(gout + (size_t)(b * 4096 + t) * FF + j0 + n * 4) = w; }
;                     pr1[0] = r1[0]; pr1[1] = r1[1]; pr2[0] = r2[0]; pr2[1] = r2[1];
;                 }
.LBB0_916:
	s_or_b64 exec, exec, s[88:89]
	v_mov_b32_e32 v205, v204
	v_pk_mul_f32 v[60:61], v[60:61], v[204:205]
	v_mov_b32_e32 v116, v204
	v_mov_b32_e32 v117, v204
	v_cndmask_b32_e64 v131, v60, 0, s[78:79]
	v_pk_mul_f32 v[62:63], v[62:63], v[116:117]
	v_cndmask_b32_e64 v130, v61, 0, s[78:79]
	v_mov_b32_dpp v122, v131 row_ror:1 row_mask:0xf bank_mask:0xf
	v_cndmask_b32_e64 v127, v62, 0, s[78:79]
	v_mov_b32_dpp v123, v131 row_ror:2 row_mask:0xf bank_mask:0xf
	v_mov_b32_dpp v120, v130 row_ror:1 row_mask:0xf bank_mask:0xf
	s_waitcnt lgkmcnt(1)
	v_cndmask_b32_e64 v104, v122, v104, s[8:9]
	v_pk_mul_f32 v[58:59], v[58:59], v[116:117]
	v_pk_mul_f32 v[56:57], v[56:57], v[116:117]
	v_cndmask_b32_e64 v126, v63, 0, s[78:79]
	v_mov_b32_dpp v121, v130 row_ror:2 row_mask:0xf bank_mask:0xf
	v_mov_b32_dpp v118, v127 row_ror:1 row_mask:0xf bank_mask:0xf
	v_cndmask_b32_e64 v108, v108, v123, s[10:11]
	s_waitcnt vmcnt(4)
	v_fma_f32 v131, v96, v131, v100
	v_cndmask_b32_e64 v105, v120, v105, s[8:9]
	v_fma_f32 v104, v92, v104, v131
	v_cndmask_b32_e64 v129, v56, 0, s[78:79]
	v_mov_b32_dpp v119, v127 row_ror:2 row_mask:0xf bank_mask:0xf
	v_mov_b32_dpp v116, v126 row_ror:1 row_mask:0xf bank_mask:0xf
	v_fma_f32 v104, v88, v108, v104
	v_cndmask_b32_e64 v108, v109, v121, s[10:11]
	v_fma_f32 v109, v97, v130, v101
	v_cndmask_b32_e64 v106, v118, v106, s[8:9]
	v_fma_f32 v105, v93, v105, v109
	v_mov_b32_dpp v117, v126 row_ror:2 row_mask:0xf bank_mask:0xf
	v_mov_b32_dpp v62, v129 row_ror:1 row_mask:0xf bank_mask:0xf
	v_fma_f32 v105, v89, v108, v105
	v_cndmask_b32_e64 v108, v110, v119, s[10:11]
	v_fma_f32 v109, v98, v127, v102
	v_cndmask_b32_e64 v107, v116, v107, s[8:9]
	v_fma_f32 v106, v94, v106, v109
	v_cndmask_b32_e64 v128, v57, 0, s[78:79]
	v_mov_b32_dpp v63, v129 row_ror:2 row_mask:0xf bank_mask:0xf
	v_fma_f32 v106, v90, v108, v106
	v_cndmask_b32_e64 v108, v111, v117, s[10:11]
	v_fma_f32 v109, v99, v126, v103
	s_waitcnt lgkmcnt(0)
	v_cndmask_b32_e64 v64, v62, v64, s[8:9]
	v_fma_f32 v107, v95, v107, v109
	v_cndmask_b32_e64 v124, v59, 0, s[78:79]
	v_cndmask_b32_e64 v125, v58, 0, s[78:79]
	v_mov_b32_dpp v60, v128 row_ror:1 row_mask:0xf bank_mask:0xf
	v_mov_b32_dpp v61, v128 row_ror:2 row_mask:0xf bank_mask:0xf
	v_fma_f32 v107, v91, v108, v107
	v_cndmask_b32_e64 v76, v76, v63, s[10:11]
	s_waitcnt vmcnt(0)
	v_fma_f32 v108, v80, v129, v84
	v_mov_b32_dpp v58, v125 row_ror:1 row_mask:0xf bank_mask:0xf
	v_fma_f32 v64, v72, v64, v108
	v_mov_b32_dpp v56, v124 row_ror:1 row_mask:0xf bank_mask:0xf
	v_fma_f32 v64, v68, v76, v64
	v_cndmask_b32_e64 v65, v60, v65, s[8:9]
	v_cndmask_b32_e64 v76, v77, v61, s[10:11]
	v_fma_f32 v77, v81, v128, v85
	v_mov_b32_dpp v59, v125 row_ror:2 row_mask:0xf bank_mask:0xf
	v_fma_f32 v65, v73, v65, v77
	v_cndmask_b32_e64 v66, v58, v66, s[8:9]
	v_fma_f32 v77, v82, v125, v86
	v_cndmask_b32_e64 v67, v56, v67, s[8:9]
	v_mov_b32_dpp v57, v124 row_ror:2 row_mask:0xf bank_mask:0xf
	v_fma_f32 v65, v69, v76, v65
	v_cndmask_b32_e64 v76, v78, v59, s[10:11]
	v_fma_f32 v66, v74, v66, v77
	v_fma_f32 v77, v83, v124, v87
	s_nop 0
	v_fma_f32 v67, v75, v67, v77
	v_fma_f32 v66, v70, v76, v66
	v_cndmask_b32_e64 v76, v79, v57, s[10:11]
	v_fma_f32 v67, v71, v76, v67
	s_and_saveexec_b64 s[78:79], s[80:81]
	s_cbranch_execz .LBB0_918
	v_mul_f32_e32 v76, 0xbfb8aa3b, v107
	v_exp_f32_e32 v76, v76
	s_nop 0
	v_add_f32_e32 v76, 1.0, v76
	v_rcp_f32_e32 v76, v76
	s_nop 0
	v_mul_f32_e32 v76, v107, v76
	v_mul_f32_e32 v67, v76, v67
	v_mul_f32_e32 v76, 0xbfb8aa3b, v106
	v_exp_f32_e32 v76, v76
	s_nop 0
	v_add_f32_e32 v76, 1.0, v76
	v_rcp_f32_e32 v76, v76
	s_nop 0
	v_mul_f32_e32 v76, v106, v76
	v_mul_f32_e32 v66, v76, v66
	v_mul_f32_e32 v76, 0xbfb8aa3b, v105
	v_exp_f32_e32 v76, v76
	s_nop 0
	v_add_f32_e32 v76, 1.0, v76
	v_rcp_f32_e32 v76, v76
	s_nop 0
	v_mul_f32_e32 v76, v105, v76
	v_mul_f32_e32 v65, v76, v65
	v_mul_f32_e32 v76, 0xbfb8aa3b, v104
	v_exp_f32_e32 v76, v76
	s_nop 0
	v_add_f32_e32 v76, 1.0, v76
	v_rcp_f32_e32 v76, v76
	s_nop 0
	v_mul_f32_e32 v76, v104, v76
	v_mul_f32_e32 v64, v76, v64
	v_cvt_pk_bf16_f32 v64, v64, v65
	v_cvt_pk_bf16_f32 v65, v66, v67
	v_mul_u32_u24_e32 v66, s69, v199
	v_lshl_add_u32 v66, v192, 1, v66
	global_store_dwordx2 v66, v[64:65], s[36:37] offset:8
.LBB0_918:
	s_or_b64 exec, exec, s[78:79]
	v_mov_b32_e32 v201, v200
	v_mov_b32_e32 v64, v200
	v_mov_b32_e32 v65, v200
	v_pk_mul_f32 v[106:107], v[54:55], v[64:65]
	v_pk_mul_f32 v[110:111], v[48:49], v[200:201]
	v_pk_mul_f32 v[104:105], v[52:53], v[200:201]
	v_pk_mul_f32 v[108:109], v[50:51], v[64:65]
	v_mov_b32_dpp v54, v110 row_ror:1 row_mask:0xf bank_mask:0xf
	v_mov_b32_dpp v64, v110 row_ror:2 row_mask:0xf bank_mask:0xf
	v_mov_b32_dpp v52, v111 row_ror:1 row_mask:0xf bank_mask:0xf
	v_cndmask_b32_e64 v62, v54, v62, s[8:9]
	v_mov_b32_dpp v53, v111 row_ror:2 row_mask:0xf bank_mask:0xf
	v_mov_b32_dpp v50, v108 row_ror:1 row_mask:0xf bank_mask:0xf
	v_cndmask_b32_e64 v63, v63, v64, s[10:11]
	v_fma_f32 v110, v80, v110, v84
	v_cndmask_b32_e64 v60, v52, v60, s[8:9]
	v_fma_f32 v62, v72, v62, v110
	v_mov_b32_dpp v51, v108 row_ror:2 row_mask:0xf bank_mask:0xf
	v_mov_b32_dpp v48, v109 row_ror:1 row_mask:0xf bank_mask:0xf
	v_fma_f32 v62, v68, v63, v62
	v_cndmask_b32_e64 v61, v61, v53, s[10:11]
	v_fma_f32 v63, v81, v111, v85
	v_cndmask_b32_e64 v58, v50, v58, s[8:9]
	v_fma_f32 v60, v73, v60, v63
	v_mov_b32_dpp v78, v104 row_ror:1 row_mask:0xf bank_mask:0xf
	v_mov_b32_dpp v79, v104 row_ror:2 row_mask:0xf bank_mask:0xf
	v_mov_b32_dpp v76, v105 row_ror:1 row_mask:0xf bank_mask:0xf
	v_mov_b32_dpp v77, v105 row_ror:2 row_mask:0xf bank_mask:0xf
	v_mov_b32_dpp v66, v106 row_ror:1 row_mask:0xf bank_mask:0xf
	v_mov_b32_dpp v67, v106 row_ror:2 row_mask:0xf bank_mask:0xf
	v_mov_b32_dpp v55, v107 row_ror:1 row_mask:0xf bank_mask:0xf
	v_mov_b32_dpp v65, v107 row_ror:2 row_mask:0xf bank_mask:0xf
	v_fma_f32 v104, v96, v104, v100
	v_fma_f32 v105, v97, v105, v101
	v_fma_f32 v106, v98, v106, v102
	v_fma_f32 v107, v99, v107, v103
	v_fma_f32 v60, v69, v61, v60
	v_cndmask_b32_e64 v59, v59, v51, s[10:11]
	v_fma_f32 v61, v82, v108, v86
	v_cndmask_b32_e64 v56, v48, v56, s[8:9]
	v_fma_f32 v58, v74, v58, v61
	v_mov_b32_dpp v49, v109 row_ror:2 row_mask:0xf bank_mask:0xf
	v_cndmask_b32_e64 v122, v78, v122, s[8:9]
	v_fma_f32 v104, v92, v122, v104
	v_cndmask_b32_e64 v120, v76, v120, s[8:9]
	v_fma_f32 v105, v93, v120, v105
	v_cndmask_b32_e64 v118, v66, v118, s[8:9]
	v_fma_f32 v106, v94, v118, v106
	v_cndmask_b32_e64 v116, v55, v116, s[8:9]
	v_fma_f32 v107, v95, v116, v107
	v_fma_f32 v58, v70, v59, v58
	v_fma_f32 v59, v83, v109, v87
	v_cndmask_b32_e64 v123, v123, v79, s[10:11]
	v_fma_f32 v56, v75, v56, v59
	v_fma_f32 v104, v88, v123, v104
	v_cndmask_b32_e64 v121, v121, v77, s[10:11]
	v_fma_f32 v105, v89, v121, v105
	v_cndmask_b32_e64 v119, v119, v67, s[10:11]
	v_fma_f32 v106, v90, v119, v106
	v_cndmask_b32_e64 v117, v117, v65, s[10:11]
	v_fma_f32 v107, v91, v117, v107
	v_cndmask_b32_e64 v57, v57, v49, s[10:11]
	v_fma_f32 v56, v71, v57, v56
	s_and_saveexec_b64 s[78:79], s[66:67]
	s_cbranch_execz .LBB0_920
; __device__ __forceinline__ unsigned cvt_pk_bf16(float lo, float hi) { unsigned r; asm volatile("v_cvt_pk_bf16_f32 %0, %1, %2" : "=v"(r) : "v"(lo), "v"(hi)); return r; }
; __device__ __forceinline__ float sigmoid_f(float x) { return __builtin_amdgcn_rcpf(1.0f + __builtin_amdgcn_exp2f(-1.4426950408889634f * x)); }
; __device__ __forceinline__ float dpp_ror1(float v) { return __builtin_bit_cast(float, __builtin_amdgcn_update_dpp(0, __builtin_bit_cast(int, v), 0x121, 0xf, 0xf, false)); }
; __device__ __forceinline__ float dpp_ror2(float v) { return __builtin_bit_cast(float, __builtin_amdgcn_update_dpp(0, __builtin_bit_cast(int, v), 0x122, 0xf, 0xf, false)); }
; __device__ __forceinline__ float fma_s(float a, float b, float c) { float r; asm("v_fma_f32 %0, %1, %2, %3" : "=v"(r) : "v"(a), "v"(b), "v"(c)); return r; }
;     __device__ __forceinline__ void operator()(const f32x4 (&acc)[2][2][4][2], const Unit& u, int wr, int wc, int fr, int fq) const {
;     ...
;                 for (int m = 0; m < 4; ++m) {
;                     f32x4 cur[2] = {acc[ai][0][m][n] * r2v[ai][m], acc[ai][1][m][n] * r2v[ai][m]};
;                     if (first && ai == 0 && wr == 0 && m == 0 && fr < 2) { cur[0] = zero4; cur[1] = zero4; }
;                     f32x4 r1[2], r2[2], av[2];
; #pragma unroll
;                     for (int bj = 0; bj < 2; ++bj)
; #pragma unroll
;                         for (int e = 0; e < 4; ++e) { r1[bj][e] = dpp_ror1(cur[bj][e]); r2[bj][e] = dpp_ror2(cur[bj][e]); }
; #pragma unroll
;                     for (int bj = 0; bj < 2; ++bj)
; #pragma unroll
;                         for (int e = 0; e < 4; ++e) { const float p1 = fr >= 1 ? r1[bj][e] : pr1[bj][e], p2 = fr >= 2 ? r2[bj][e] : pr2[bj][e];
;                             av[bj][e] = fma_s(w0[bj][e], p2, fma_s(w1[bj][e], p1, fma_s(w2[bj][e], cur[bj][e], bb[bj][e]))); }
;                     float o[4];
; #pragma unroll
;                     for (int e = 0; e < 4; ++e) o[e] = av[0][e] * sigmoid_f(av[0][e]) * av[1][e];
;                     const int lr = ai * HALF + wr * 64 + m * 16 + fr, t = t0 + lr;
;                     if (lr >= 2 && t < 4096) { u32x2 w; w.x = cvt_pk_bf16(o[0], o[1]); w.y = cvt_pk_bf16(o[2], o[3]);
;                         *(u32x2*)(gout + (size_t)(b * 4096 + t) * FF + j0 + n * 4) = w; }
;                     pr1[0] = r1[0]; pr1[1] = r1[1]; pr2[0] = r2[0]; pr2[1] = r2[1];
;                 }
	v_mul_f32_e32 v57, 0xbfb8aa3b, v107
	v_exp_f32_e32 v57, v57
	v_mul_f32_e32 v59, 0xbfb8aa3b, v104
	v_exp_f32_e32 v59, v59
	v_add_f32_e32 v57, 1.0, v57
	v_rcp_f32_e32 v57, v57
	v_add_f32_e32 v59, 1.0, v59
	v_rcp_f32_e32 v59, v59
	v_mul_f32_e32 v57, v107, v57
	v_mul_f32_e32 v57, v57, v56
	v_mul_f32_e32 v56, 0xbfb8aa3b, v106
	v_exp_f32_e32 v56, v56
	v_mul_f32_e32 v59, v104, v59
	v_mul_f32_e32 v59, v59, v62
	v_add_f32_e32 v56, 1.0, v56
	v_rcp_f32_e32 v56, v56
	s_nop 0
	v_mul_f32_e32 v56, v106, v56
	v_mul_f32_e32 v58, v56, v58
	v_mul_f32_e32 v56, 0xbfb8aa3b, v105
	v_exp_f32_e32 v56, v56
	s_nop 0
	v_add_f32_e32 v56, 1.0, v56
	v_rcp_f32_e32 v56, v56
	s_nop 0
	v_mul_f32_e32 v56, v105, v56
	v_mul_f32_e32 v56, v56, v60
	v_cvt_pk_bf16_f32 v56, v59, v56
	v_cvt_pk_bf16_f32 v57, v58, v57
	v_mul_u32_u24_e32 v58, s69, v197
	v_lshl_add_u32 v58, v192, 1, v58
	global_store_dwordx2 v58, v[56:57], s[36:37] offset:8
.LBB0_920:
	s_or_b64 exec, exec, s[78:79]
	v_mov_b32_e32 v199, v198
	v_pk_mul_f32 v[106:107], v[44:45], v[198:199]
	v_mov_b32_e32 v56, v198
	v_mov_b32_e32 v57, v198
	v_mov_b32_dpp v62, v106 row_ror:1 row_mask:0xf bank_mask:0xf
	v_pk_mul_f32 v[104:105], v[46:47], v[56:57]
	v_mov_b32_dpp v63, v106 row_ror:2 row_mask:0xf bank_mask:0xf
	v_mov_b32_dpp v60, v107 row_ror:1 row_mask:0xf bank_mask:0xf
	v_cndmask_b32_e64 v78, v62, v78, s[8:9]
	v_mov_b32_dpp v61, v107 row_ror:2 row_mask:0xf bank_mask:0xf
	v_mov_b32_dpp v58, v104 row_ror:1 row_mask:0xf bank_mask:0xf
	v_cndmask_b32_e64 v79, v79, v63, s[10:11]
	v_fma_f32 v106, v96, v106, v100
	v_cndmask_b32_e64 v76, v60, v76, s[8:9]
	v_fma_f32 v78, v92, v78, v106
	v_pk_mul_f32 v[108:109], v[42:43], v[56:57]
	v_pk_mul_f32 v[110:111], v[40:41], v[198:199]
	v_mov_b32_dpp v59, v104 row_ror:2 row_mask:0xf bank_mask:0xf
	v_mov_b32_dpp v47, v105 row_ror:1 row_mask:0xf bank_mask:0xf
	v_fma_f32 v78, v88, v79, v78
	v_cndmask_b32_e64 v77, v77, v61, s[10:11]
	v_fma_f32 v79, v97, v107, v101
	v_cndmask_b32_e64 v66, v58, v66, s[8:9]
	v_fma_f32 v76, v93, v76, v79
	v_mov_b32_dpp v57, v105 row_ror:2 row_mask:0xf bank_mask:0xf
	v_mov_b32_dpp v46, v110 row_ror:1 row_mask:0xf bank_mask:0xf
	v_fma_f32 v76, v89, v77, v76
	v_cndmask_b32_e64 v67, v67, v59, s[10:11]
	v_fma_f32 v77, v98, v104, v102
	v_cndmask_b32_e64 v55, v47, v55, s[8:9]
	v_fma_f32 v66, v94, v66, v77
	v_mov_b32_dpp v56, v110 row_ror:2 row_mask:0xf bank_mask:0xf
	v_mov_b32_dpp v44, v111 row_ror:1 row_mask:0xf bank_mask:0xf
	v_fma_f32 v66, v90, v67, v66
	v_cndmask_b32_e64 v65, v65, v57, s[10:11]
	v_fma_f32 v67, v99, v105, v103
	v_cndmask_b32_e64 v54, v46, v54, s[8:9]
	v_fma_f32 v55, v95, v55, v67
	v_mov_b32_dpp v45, v111 row_ror:2 row_mask:0xf bank_mask:0xf
	v_mov_b32_dpp v42, v108 row_ror:1 row_mask:0xf bank_mask:0xf
	v_fma_f32 v55, v91, v65, v55
	v_cndmask_b32_e64 v64, v64, v56, s[10:11]
	v_fma_f32 v65, v80, v110, v84
	v_cndmask_b32_e64 v52, v44, v52, s[8:9]
	v_fma_f32 v54, v72, v54, v65
	v_mov_b32_dpp v43, v108 row_ror:2 row_mask:0xf bank_mask:0xf
	v_mov_b32_dpp v40, v109 row_ror:1 row_mask:0xf bank_mask:0xf
	v_fma_f32 v54, v68, v64, v54
	v_cndmask_b32_e64 v53, v53, v45, s[10:11]
	v_fma_f32 v64, v81, v111, v85
	v_cndmask_b32_e64 v50, v42, v50, s[8:9]
	v_fma_f32 v52, v73, v52, v64
	v_fma_f32 v52, v69, v53, v52
	v_cndmask_b32_e64 v51, v51, v43, s[10:11]
	v_fma_f32 v53, v82, v108, v86
	v_cndmask_b32_e64 v48, v40, v48, s[8:9]
	v_fma_f32 v50, v74, v50, v53
	v_mov_b32_dpp v41, v109 row_ror:2 row_mask:0xf bank_mask:0xf
	v_fma_f32 v50, v70, v51, v50
	v_fma_f32 v51, v83, v109, v87
	v_cndmask_b32_e64 v49, v49, v41, s[10:11]
	v_fma_f32 v48, v75, v48, v51
	s_nop 0
	v_fma_f32 v48, v71, v49, v48
	s_and_saveexec_b64 s[66:67], s[0:1]
	s_cbranch_execz .LBB0_922
	v_mul_f32_e32 v49, 0xbfb8aa3b, v55
	v_exp_f32_e32 v49, v49
	v_mul_f32_e32 v51, 0xbfb8aa3b, v78
	v_exp_f32_e32 v51, v51
	v_add_f32_e32 v49, 1.0, v49
	v_rcp_f32_e32 v49, v49
	v_add_f32_e32 v51, 1.0, v51
	v_rcp_f32_e32 v51, v51
	v_mul_f32_e32 v49, v55, v49
	v_mul_f32_e32 v49, v49, v48
	v_mul_f32_e32 v48, 0xbfb8aa3b, v66
	v_exp_f32_e32 v48, v48
	v_mul_f32_e32 v51, v78, v51
	v_mul_f32_e32 v51, v51, v54
	v_add_f32_e32 v48, 1.0, v48
	v_rcp_f32_e32 v48, v48
	s_nop 0
	v_mul_f32_e32 v48, v66, v48
	v_mul_f32_e32 v50, v48, v50
	v_mul_f32_e32 v48, 0xbfb8aa3b, v76
	v_exp_f32_e32 v48, v48
	s_nop 0
	v_add_f32_e32 v48, 1.0, v48
	v_rcp_f32_e32 v48, v48
	s_nop 0
	v_mul_f32_e32 v48, v76, v48
	v_mul_f32_e32 v48, v48, v52
	v_cvt_pk_bf16_f32 v48, v51, v48
	v_cvt_pk_bf16_f32 v49, v50, v49
	v_mul_u32_u24_e32 v50, s69, v195
	v_lshl_add_u32 v50, v192, 1, v50
	global_store_dwordx2 v50, v[48:49], s[36:37] offset:8
; #define PG8_LAS __attribute__((address_space(3)))
; __device__ __forceinline__ unsigned cvt_pk_bf16(float lo, float hi) { unsigned r; asm volatile("v_cvt_pk_bf16_f32 %0, %1, %2" : "=v"(r) : "v"(lo), "v"(hi)); return r; }
;     __device__ __forceinline__ void operator()(const f32x4 (&acc)[2][2][4][2], const Unit& u, int wr, int wc, int fr, int fq) const {
;     ...
;                 f32x4 pr1[2] = {zero4, zero4}, pr2[2] = {zero4, zero4};
;                 const bool hasprev = (wr == 1) || (ai == 1);
;                 const int pg = (wr == 1) ? ai * 2 : (ai - 1) * 2 + 1;
;                 if (hasprev && fr < 2) {
; #pragma unroll
;                     for (int bj = 0; bj < 2; ++bj) {
;                         pr2[bj] = *(const PG8_LAS f32x4*)(xch + ((pg * 2 + fr) * 256 + bj * 128 + colx + n * 4));
;                         pr1[bj] = *(const PG8_LAS f32x4*)(xch + ((pg * 2 + 1) * 256 + bj * 128 + colx + n * 4)); }
;                 }
; #pragma unroll
;                 for (int m = 0; m < 4; ++m) {
;                     f32x4 cur[2] = {acc[ai][0][m][n] * r2v[ai][m], acc[ai][1][m][n] * r2v[ai][m]};
;                     if (first && ai == 0 && wr == 0 && m == 0 && fr < 2) { cur[0] = zero4; cur[1] = zero4; }
;                     f32x4 r1[2], r2[2], av[2];
; #pragma unroll
;                     for (int bj = 0; bj < 2; ++bj)
; #pragma unroll
;                         for (int e = 0; e < 4; ++e) { r1[bj][e] = dpp_ror1(cur[bj][e]); r2[bj][e] = dpp_ror2(cur[bj][e]); }
; #pragma unroll
;                     for (int bj = 0; bj < 2; ++bj)
; #pragma unroll
;                         for (int e = 0; e < 4; ++e) { const float p1 = fr >= 1 ? r1[bj][e] : pr1[bj][e], p2 = fr >= 2 ? r2[bj][e] : pr2[bj][e];
;                             av[bj][e] = fma_s(w0[bj][e], p2, fma_s(w1[bj][e], p1, fma_s(w2[bj][e], cur[bj][e], bb[bj][e]))); }
;                     float o[4];
; #pragma unroll
;                     for (int e = 0; e < 4; ++e) o[e] = av[0][e] * sigmoid_f(av[0][e]) * av[1][e];
;                     const int lr = ai * HALF + wr * 64 + m * 16 + fr, t = t0 + lr;
;                     if (lr >= 2 && t < 4096) { u32x2 w; w.x = cvt_pk_bf16(o[0], o[1]); w.y = cvt_pk_bf16(o[2], o[3]);
;                         *(u32x2*)(gout + (size_t)(b * 4096 + t) * FF + j0 + n * 4) = w; }
;                     pr1[0] = r1[0]; pr1[1] = r1[1]; pr2[0] = r2[0]; pr2[1] = r2[1];
;                 }
.LBB0_922:
	s_or_b64 exec, exec, s[66:67]
	v_mov_b32_e32 v197, v196
	v_pk_mul_f32 v[36:37], v[36:37], v[196:197]
	v_pk_mul_f32 v[50:51], v[32:33], v[196:197]
	v_mov_b32_e32 v48, v196
	v_mov_b32_e32 v49, v196
	v_mov_b32_dpp v32, v36 row_ror:1 row_mask:0xf bank_mask:0xf
	v_pk_mul_f32 v[38:39], v[38:39], v[48:49]
	v_pk_mul_f32 v[48:49], v[34:35], v[48:49]
	v_mov_b32_dpp v33, v36 row_ror:2 row_mask:0xf bank_mask:0xf
	v_cndmask_b32_e64 v32, v32, v62, s[8:9]
	v_mov_b32_dpp v34, v37 row_ror:1 row_mask:0xf bank_mask:0xf
	v_cndmask_b32_e64 v33, v63, v33, s[10:11]
	v_fma_f32 v36, v96, v36, v100
	v_mov_b32_dpp v35, v37 row_ror:2 row_mask:0xf bank_mask:0xf
	v_fma_f32 v32, v92, v32, v36
	v_fma_f32 v32, v88, v33, v32
	v_cndmask_b32_e64 v33, v34, v60, s[8:9]
	v_mov_b32_dpp v52, v38 row_ror:1 row_mask:0xf bank_mask:0xf
	v_cndmask_b32_e64 v34, v61, v35, s[10:11]
	v_fma_f32 v35, v97, v37, v101
	v_mov_b32_dpp v53, v38 row_ror:2 row_mask:0xf bank_mask:0xf
	v_fma_f32 v33, v93, v33, v35
	v_fma_f32 v33, v89, v34, v33
	v_cndmask_b32_e64 v34, v52, v58, s[8:9]
	v_mov_b32_dpp v54, v39 row_ror:1 row_mask:0xf bank_mask:0xf
	v_cndmask_b32_e64 v35, v59, v53, s[10:11]
	v_fma_f32 v36, v98, v38, v102
	v_mov_b32_dpp v55, v39 row_ror:2 row_mask:0xf bank_mask:0xf
	v_fma_f32 v34, v94, v34, v36
	v_fma_f32 v34, v90, v35, v34
	v_cndmask_b32_e64 v35, v54, v47, s[8:9]
	v_mov_b32_dpp v64, v50 row_ror:1 row_mask:0xf bank_mask:0xf
	v_cndmask_b32_e64 v36, v57, v55, s[10:11]
	v_fma_f32 v37, v99, v39, v103
	v_mov_b32_dpp v65, v50 row_ror:2 row_mask:0xf bank_mask:0xf
	v_fma_f32 v35, v95, v35, v37
	v_fma_f32 v36, v91, v36, v35
	v_cndmask_b32_e64 v35, v64, v46, s[8:9]
	v_mov_b32_dpp v66, v51 row_ror:1 row_mask:0xf bank_mask:0xf
	v_cndmask_b32_e64 v37, v56, v65, s[10:11]
	v_fma_f32 v38, v80, v50, v84
	v_mov_b32_dpp v67, v51 row_ror:2 row_mask:0xf bank_mask:0xf
	v_fma_f32 v35, v72, v35, v38
	v_fma_f32 v35, v68, v37, v35
	v_cndmask_b32_e64 v37, v66, v44, s[8:9]
	v_mov_b32_dpp v76, v48 row_ror:1 row_mask:0xf bank_mask:0xf
	v_cndmask_b32_e64 v38, v45, v67, s[10:11]
	v_fma_f32 v39, v81, v51, v85
	v_mov_b32_dpp v77, v48 row_ror:2 row_mask:0xf bank_mask:0xf
	v_fma_f32 v37, v73, v37, v39
	v_fma_f32 v37, v69, v38, v37
	v_cndmask_b32_e64 v38, v76, v42, s[8:9]
	v_mov_b32_dpp v78, v49 row_ror:1 row_mask:0xf bank_mask:0xf
	v_cndmask_b32_e64 v39, v43, v77, s[10:11]
	v_fma_f32 v42, v82, v48, v86
	v_mov_b32_dpp v79, v49 row_ror:2 row_mask:0xf bank_mask:0xf
	v_fma_f32 v38, v74, v38, v42
	s_nop 0
	v_fma_f32 v38, v70, v39, v38
	v_cndmask_b32_e64 v39, v78, v40, s[8:9]
	v_cndmask_b32_e64 v40, v41, v79, s[10:11]
	v_fma_f32 v41, v83, v49, v87
	s_nop 0
	v_fma_f32 v39, v75, v39, v41
	s_nop 0
	v_fma_f32 v39, v71, v40, v39
	s_and_saveexec_b64 s[0:1], s[64:65]
	s_cbranch_execz .LBB0_924
	v_mul_f32_e32 v40, 0xbfb8aa3b, v36
	v_exp_f32_e32 v40, v40
	v_mul_f32_e32 v41, 0xbfb8aa3b, v34
	v_mul_f32_e32 v42, 0xbfb8aa3b, v33
	v_exp_f32_e32 v41, v41
	v_add_f32_e32 v40, 1.0, v40
	v_rcp_f32_e32 v40, v40
	v_exp_f32_e32 v42, v42
	v_add_f32_e32 v41, 1.0, v41
	v_rcp_f32_e32 v41, v41
	v_mul_f32_e32 v36, v36, v40
	v_mul_f32_e32 v36, v36, v39
	v_mul_f32_e32 v39, 0xbfb8aa3b, v32
	v_exp_f32_e32 v39, v39
	v_add_f32_e32 v40, 1.0, v42
	v_rcp_f32_e32 v40, v40
	v_mul_f32_e32 v34, v34, v41
	v_add_f32_e32 v39, 1.0, v39
	v_rcp_f32_e32 v39, v39
	v_mul_f32_e32 v33, v33, v40
	v_mul_f32_e32 v34, v34, v38
	v_mul_f32_e32 v33, v33, v37
	v_mul_f32_e32 v32, v32, v39
	v_mul_f32_e32 v32, v32, v35
	v_cvt_pk_bf16_f32 v32, v32, v33
	v_cvt_pk_bf16_f32 v33, v34, v36
	v_mul_u32_u24_e32 v34, s69, v227
	v_lshl_add_u32 v34, v192, 1, v34
	global_store_dwordx2 v34, v[32:33], s[36:37] offset:8
.LBB0_924:
	s_or_b64 exec, exec, s[0:1]
	v_mov_b64_e32 v[32:33], 0
	v_mov_b64_e32 v[34:35], 0
	v_mov_b64_e32 v[40:41], 0
	v_mov_b64_e32 v[42:43], 0
	v_mov_b64_e32 v[36:37], 0
	v_mov_b64_e32 v[38:39], 0
	v_mov_b64_e32 v[44:45], 0
	v_mov_b64_e32 v[46:47], 0
	s_and_saveexec_b64 s[0:1], s[6:7]
	s_cbranch_execz .LBB0_926
	ds_read_b128 v[44:47], v220 offset:16
	ds_read_b128 v[36:39], v220 offset:528
	ds_read_b128 v[40:43], v219 offset:1040
	ds_read_b128 v[32:35], v219 offset:1552
.LBB0_926:
	s_or_b64 exec, exec, s[0:1]
	v_mov_b32_e32 v203, v202
	v_pk_mul_f32 v[58:59], v[28:29], v[202:203]
	v_mov_b32_e32 v48, v202
	v_mov_b32_e32 v49, v202
	v_mov_b32_dpp v54, v58 row_ror:1 row_mask:0xf bank_mask:0xf
	v_pk_mul_f32 v[56:57], v[30:31], v[48:49]
	v_mov_b32_dpp v55, v58 row_ror:2 row_mask:0xf bank_mask:0xf
	v_mov_b32_dpp v52, v59 row_ror:1 row_mask:0xf bank_mask:0xf
	s_waitcnt lgkmcnt(1)
	v_cndmask_b32_e64 v40, v54, v40, s[8:9]
	v_mov_b32_dpp v53, v59 row_ror:2 row_mask:0xf bank_mask:0xf
	v_mov_b32_dpp v50, v56 row_ror:1 row_mask:0xf bank_mask:0xf
	v_cndmask_b32_e64 v44, v44, v55, s[10:11]
	v_fma_f32 v58, v96, v58, v100
	v_cndmask_b32_e64 v41, v52, v41, s[8:9]
	v_fma_f32 v40, v92, v40, v58
	v_pk_mul_f32 v[60:61], v[26:27], v[48:49]
	v_pk_mul_f32 v[62:63], v[24:25], v[202:203]
	v_mov_b32_dpp v51, v56 row_ror:2 row_mask:0xf bank_mask:0xf
	v_mov_b32_dpp v31, v57 row_ror:1 row_mask:0xf bank_mask:0xf
	v_fma_f32 v40, v88, v44, v40
	v_cndmask_b32_e64 v44, v45, v53, s[10:11]
	v_fma_f32 v45, v97, v59, v101
	v_cndmask_b32_e64 v42, v50, v42, s[8:9]
	v_fma_f32 v41, v93, v41, v45
	v_mov_b32_dpp v49, v57 row_ror:2 row_mask:0xf bank_mask:0xf
	v_mov_b32_dpp v30, v62 row_ror:1 row_mask:0xf bank_mask:0xf
	v_fma_f32 v41, v89, v44, v41
	v_cndmask_b32_e64 v44, v46, v51, s[10:11]
	v_fma_f32 v45, v98, v56, v102
	v_cndmask_b32_e64 v43, v31, v43, s[8:9]
	v_fma_f32 v42, v94, v42, v45
	v_mov_b32_dpp v48, v62 row_ror:2 row_mask:0xf bank_mask:0xf
	v_fma_f32 v42, v90, v44, v42
	v_cndmask_b32_e64 v44, v47, v49, s[10:11]
	v_fma_f32 v45, v99, v57, v103
	s_waitcnt lgkmcnt(0)
	v_cndmask_b32_e64 v32, v30, v32, s[8:9]
	v_fma_f32 v43, v95, v43, v45
	v_mov_b32_dpp v28, v63 row_ror:1 row_mask:0xf bank_mask:0xf
	v_mov_b32_dpp v29, v63 row_ror:2 row_mask:0xf bank_mask:0xf
	v_fma_f32 v43, v91, v44, v43
	v_cndmask_b32_e64 v36, v36, v48, s[10:11]
	v_fma_f32 v44, v80, v62, v84
	v_mov_b32_dpp v26, v60 row_ror:1 row_mask:0xf bank_mask:0xf
	v_fma_f32 v32, v72, v32, v44
	v_mov_b32_dpp v24, v61 row_ror:1 row_mask:0xf bank_mask:0xf
	v_fma_f32 v32, v68, v36, v32
	v_cndmask_b32_e64 v33, v28, v33, s[8:9]
	v_cndmask_b32_e64 v36, v37, v29, s[10:11]
	v_fma_f32 v37, v81, v63, v85
	v_mov_b32_dpp v27, v60 row_ror:2 row_mask:0xf bank_mask:0xf
	v_fma_f32 v33, v73, v33, v37
	v_cndmask_b32_e64 v34, v26, v34, s[8:9]
	v_fma_f32 v37, v82, v60, v86
	v_cndmask_b32_e64 v35, v24, v35, s[8:9]
	v_mov_b32_dpp v25, v61 row_ror:2 row_mask:0xf bank_mask:0xf
	v_fma_f32 v33, v69, v36, v33
	v_cndmask_b32_e64 v36, v38, v27, s[10:11]
	v_fma_f32 v34, v74, v34, v37
	v_fma_f32 v37, v83, v61, v87
	s_nop 0
	v_fma_f32 v35, v75, v35, v37
	v_fma_f32 v34, v70, v36, v34
	v_cndmask_b32_e64 v36, v39, v25, s[10:11]
	v_fma_f32 v35, v71, v36, v35
	s_and_saveexec_b64 s[0:1], s[76:77]
	s_cbranch_execz .LBB0_928
; __device__ __forceinline__ unsigned cvt_pk_bf16(float lo, float hi) { unsigned r; asm volatile("v_cvt_pk_bf16_f32 %0, %1, %2" : "=v"(r) : "v"(lo), "v"(hi)); return r; }
; __device__ __forceinline__ float sigmoid_f(float x) { return __builtin_amdgcn_rcpf(1.0f + __builtin_amdgcn_exp2f(-1.4426950408889634f * x)); }
; __device__ __forceinline__ float dpp_ror1(float v) { return __builtin_bit_cast(float, __builtin_amdgcn_update_dpp(0, __builtin_bit_cast(int, v), 0x121, 0xf, 0xf, false)); }
; __device__ __forceinline__ float dpp_ror2(float v) { return __builtin_bit_cast(float, __builtin_amdgcn_update_dpp(0, __builtin_bit_cast(int, v), 0x122, 0xf, 0xf, false)); }
; __device__ __forceinline__ float fma_s(float a, float b, float c) { float r; asm("v_fma_f32 %0, %1, %2, %3" : "=v"(r) : "v"(a), "v"(b), "v"(c)); return r; }
;     __device__ __forceinline__ void operator()(const f32x4 (&acc)[2][2][4][2], const Unit& u, int wr, int wc, int fr, int fq) const {
;     ...
;                 for (int m = 0; m < 4; ++m) {
;                     f32x4 cur[2] = {acc[ai][0][m][n] * r2v[ai][m], acc[ai][1][m][n] * r2v[ai][m]};
;                     if (first && ai == 0 && wr == 0 && m == 0 && fr < 2) { cur[0] = zero4; cur[1] = zero4; }
;                     f32x4 r1[2], r2[2], av[2];
; #pragma unroll
;                     for (int bj = 0; bj < 2; ++bj)
; #pragma unroll
;                         for (int e = 0; e < 4; ++e) { r1[bj][e] = dpp_ror1(cur[bj][e]); r2[bj][e] = dpp_ror2(cur[bj][e]); }
; #pragma unroll
;                     for (int bj = 0; bj < 2; ++bj)
; #pragma unroll
;                         for (int e = 0; e < 4; ++e) { const float p1 = fr >= 1 ? r1[bj][e] : pr1[bj][e], p2 = fr >= 2 ? r2[bj][e] : pr2[bj][e];
;                             av[bj][e] = fma_s(w0[bj][e], p2, fma_s(w1[bj][e], p1, fma_s(w2[bj][e], cur[bj][e], bb[bj][e]))); }
;                     float o[4];
; #pragma unroll
;                     for (int e = 0; e < 4; ++e) o[e] = av[0][e] * sigmoid_f(av[0][e]) * av[1][e];
;                     const int lr = ai * HALF + wr * 64 + m * 16 + fr, t = t0 + lr;
;                     if (lr >= 2 && t < 4096) { u32x2 w; w.x = cvt_pk_bf16(o[0], o[1]); w.y = cvt_pk_bf16(o[2], o[3]);
;                         *(u32x2*)(gout + (size_t)(b * 4096 + t) * FF + j0 + n * 4) = w; }
;                     pr1[0] = r1[0]; pr1[1] = r1[1]; pr2[0] = r2[0]; pr2[1] = r2[1];
;                 }
	v_mul_f32_e32 v36, 0xbfb8aa3b, v43
	v_exp_f32_e32 v36, v36
	v_mul_f32_e32 v37, 0xbfb8aa3b, v42
	v_mul_f32_e32 v38, 0xbfb8aa3b, v41
	v_exp_f32_e32 v37, v37
	v_add_f32_e32 v36, 1.0, v36
	v_rcp_f32_e32 v36, v36
	v_exp_f32_e32 v38, v38
	v_add_f32_e32 v37, 1.0, v37
	v_rcp_f32_e32 v37, v37
	v_mul_f32_e32 v36, v43, v36
	v_mul_f32_e32 v35, v36, v35
	v_mul_f32_e32 v36, 0xbfb8aa3b, v40
	v_exp_f32_e32 v36, v36
	v_add_f32_e32 v38, 1.0, v38
	v_rcp_f32_e32 v38, v38
	v_mul_f32_e32 v37, v42, v37
	v_add_f32_e32 v36, 1.0, v36
	v_rcp_f32_e32 v36, v36
	v_mul_f32_e32 v34, v37, v34
	v_mul_f32_e32 v37, v41, v38
	v_mul_f32_e32 v33, v37, v33
	v_mul_f32_e32 v36, v40, v36
	v_mul_f32_e32 v32, v36, v32
	v_cvt_pk_bf16_f32 v32, v32, v33
	v_cvt_pk_bf16_f32 v33, v34, v35
	v_mul_u32_u24_e32 v34, s69, v141
	v_lshl_add_u32 v34, v192, 1, v34
	global_store_dwordx2 v34, v[32:33], s[36:37] offset:8
.LBB0_928:
	s_or_b64 exec, exec, s[0:1]
	v_mov_b32_e32 v141, v140
	v_mov_b32_e32 v32, v140
	v_mov_b32_e32 v33, v140
	v_pk_mul_f32 v[42:43], v[22:23], v[32:33]
	v_pk_mul_f32 v[46:47], v[16:17], v[140:141]
	v_pk_mul_f32 v[40:41], v[20:21], v[140:141]
	v_pk_mul_f32 v[44:45], v[18:19], v[32:33]
	v_mov_b32_dpp v23, v43 row_ror:1 row_mask:0xf bank_mask:0xf
	v_mov_b32_dpp v22, v46 row_ror:1 row_mask:0xf bank_mask:0xf
	v_mov_b32_dpp v33, v43 row_ror:2 row_mask:0xf bank_mask:0xf
	v_mov_b32_dpp v32, v46 row_ror:2 row_mask:0xf bank_mask:0xf
	v_mov_b32_dpp v20, v47 row_ror:1 row_mask:0xf bank_mask:0xf
	v_cndmask_b32_e64 v31, v23, v31, s[8:9]
	v_fma_f32 v43, v99, v43, v103
	v_cndmask_b32_e64 v30, v22, v30, s[8:9]
	v_mov_b32_dpp v21, v47 row_ror:2 row_mask:0xf bank_mask:0xf
	v_mov_b32_dpp v18, v44 row_ror:1 row_mask:0xf bank_mask:0xf
	v_fma_f32 v31, v95, v31, v43
	v_cndmask_b32_e64 v43, v48, v32, s[10:11]
	v_fma_f32 v46, v80, v46, v84
	v_cndmask_b32_e64 v28, v20, v28, s[8:9]
	v_fma_f32 v30, v72, v30, v46
	v_mov_b32_dpp v19, v44 row_ror:2 row_mask:0xf bank_mask:0xf
	v_mov_b32_dpp v16, v45 row_ror:1 row_mask:0xf bank_mask:0xf
	v_fma_f32 v30, v68, v43, v30
	v_cndmask_b32_e64 v29, v29, v21, s[10:11]
	v_fma_f32 v43, v81, v47, v85
	v_cndmask_b32_e64 v26, v18, v26, s[8:9]
	v_fma_f32 v28, v73, v28, v43
	v_mov_b32_dpp v38, v40 row_ror:1 row_mask:0xf bank_mask:0xf
	v_mov_b32_dpp v39, v40 row_ror:2 row_mask:0xf bank_mask:0xf
	v_mov_b32_dpp v36, v41 row_ror:1 row_mask:0xf bank_mask:0xf
	v_mov_b32_dpp v37, v41 row_ror:2 row_mask:0xf bank_mask:0xf
	v_mov_b32_dpp v34, v42 row_ror:1 row_mask:0xf bank_mask:0xf
	v_mov_b32_dpp v35, v42 row_ror:2 row_mask:0xf bank_mask:0xf
	v_fma_f32 v40, v96, v40, v100
	v_fma_f32 v41, v97, v41, v101
	v_fma_f32 v42, v98, v42, v102
	v_fma_f32 v28, v69, v29, v28
	v_cndmask_b32_e64 v27, v27, v19, s[10:11]
	v_fma_f32 v29, v82, v44, v86
	v_cndmask_b32_e64 v24, v16, v24, s[8:9]
	v_fma_f32 v26, v74, v26, v29
	v_mov_b32_dpp v17, v45 row_ror:2 row_mask:0xf bank_mask:0xf
	v_cndmask_b32_e64 v54, v38, v54, s[8:9]
	v_fma_f32 v40, v92, v54, v40
	v_cndmask_b32_e64 v52, v36, v52, s[8:9]
	v_fma_f32 v41, v93, v52, v41
	v_cndmask_b32_e64 v50, v34, v50, s[8:9]
	v_fma_f32 v42, v94, v50, v42
	v_fma_f32 v26, v70, v27, v26
	v_fma_f32 v27, v83, v45, v87
	v_cndmask_b32_e64 v55, v55, v39, s[10:11]
	v_fma_f32 v24, v75, v24, v27
	v_fma_f32 v40, v88, v55, v40
	v_cndmask_b32_e64 v53, v53, v37, s[10:11]
	v_fma_f32 v41, v89, v53, v41
	v_cndmask_b32_e64 v51, v51, v35, s[10:11]
	v_fma_f32 v42, v90, v51, v42
	v_cndmask_b32_e64 v49, v49, v33, s[10:11]
	v_fma_f32 v31, v91, v49, v31
	v_cndmask_b32_e64 v25, v25, v17, s[10:11]
	v_fma_f32 v24, v71, v25, v24
	s_and_saveexec_b64 s[0:1], s[82:83]
	s_cbranch_execz .LBB0_930
	v_mul_f32_e32 v25, 0xbfb8aa3b, v31
	v_exp_f32_e32 v25, v25
	v_mul_f32_e32 v27, 0xbfb8aa3b, v42
	v_mul_f32_e32 v29, 0xbfb8aa3b, v41
	v_exp_f32_e32 v27, v27
	v_add_f32_e32 v25, 1.0, v25
	v_rcp_f32_e32 v25, v25
	v_exp_f32_e32 v29, v29
	v_add_f32_e32 v27, 1.0, v27
	v_rcp_f32_e32 v27, v27
	v_mul_f32_e32 v25, v31, v25
	v_mul_f32_e32 v25, v25, v24
	v_mul_f32_e32 v24, 0xbfb8aa3b, v40
	v_exp_f32_e32 v24, v24
	v_add_f32_e32 v29, 1.0, v29
	v_rcp_f32_e32 v29, v29
	v_mul_f32_e32 v27, v42, v27
	v_add_f32_e32 v24, 1.0, v24
	v_rcp_f32_e32 v24, v24
	v_mul_f32_e32 v26, v27, v26
	v_mul_f32_e32 v27, v41, v29
	v_mul_f32_e32 v27, v27, v28
	v_mul_f32_e32 v24, v40, v24
	v_mul_f32_e32 v24, v24, v30
	v_cvt_pk_bf16_f32 v24, v24, v27
	v_cvt_pk_bf16_f32 v25, v26, v25
	v_mul_u32_u24_e32 v26, s69, v113
	v_lshl_add_u32 v26, v192, 1, v26
	global_store_dwordx2 v26, v[24:25], s[36:37] offset:8
; __device__ __forceinline__ unsigned cvt_pk_bf16(float lo, float hi) { unsigned r; asm volatile("v_cvt_pk_bf16_f32 %0, %1, %2" : "=v"(r) : "v"(lo), "v"(hi)); return r; }
; __device__ __forceinline__ float sigmoid_f(float x) { return __builtin_amdgcn_rcpf(1.0f + __builtin_amdgcn_exp2f(-1.4426950408889634f * x)); }
; __device__ __forceinline__ float dpp_ror1(float v) { return __builtin_bit_cast(float, __builtin_amdgcn_update_dpp(0, __builtin_bit_cast(int, v), 0x121, 0xf, 0xf, false)); }
; __device__ __forceinline__ float dpp_ror2(float v) { return __builtin_bit_cast(float, __builtin_amdgcn_update_dpp(0, __builtin_bit_cast(int, v), 0x122, 0xf, 0xf, false)); }
; __device__ __forceinline__ float fma_s(float a, float b, float c) { float r; asm("v_fma_f32 %0, %1, %2, %3" : "=v"(r) : "v"(a), "v"(b), "v"(c)); return r; }
;     __device__ __forceinline__ void operator()(const f32x4 (&acc)[2][2][4][2], const Unit& u, int wr, int wc, int fr, int fq) const {
;     ...
;                 for (int m = 0; m < 4; ++m) {
;                     f32x4 cur[2] = {acc[ai][0][m][n] * r2v[ai][m], acc[ai][1][m][n] * r2v[ai][m]};
;                     if (first && ai == 0 && wr == 0 && m == 0 && fr < 2) { cur[0] = zero4; cur[1] = zero4; }
;                     f32x4 r1[2], r2[2], av[2];
; #pragma unroll
;                     for (int bj = 0; bj < 2; ++bj)
; #pragma unroll
;                         for (int e = 0; e < 4; ++e) { r1[bj][e] = dpp_ror1(cur[bj][e]); r2[bj][e] = dpp_ror2(cur[bj][e]); }
; #pragma unroll
;                     for (int bj = 0; bj < 2; ++bj)
; #pragma unroll
;                         for (int e = 0; e < 4; ++e) { const float p1 = fr >= 1 ? r1[bj][e] : pr1[bj][e], p2 = fr >= 2 ? r2[bj][e] : pr2[bj][e];
;                             av[bj][e] = fma_s(w0[bj][e], p2, fma_s(w1[bj][e], p1, fma_s(w2[bj][e], cur[bj][e], bb[bj][e]))); }
;                     float o[4];
; #pragma unroll
;                     for (int e = 0; e < 4; ++e) o[e] = av[0][e] * sigmoid_f(av[0][e]) * av[1][e];
;                     const int lr = ai * HALF + wr * 64 + m * 16 + fr, t = t0 + lr;
;                     if (lr >= 2 && t < 4096) { u32x2 w; w.x = cvt_pk_bf16(o[0], o[1]); w.y = cvt_pk_bf16(o[2], o[3]);
;                         *(u32x2*)(gout + (size_t)(b * 4096 + t) * FF + j0 + n * 4) = w; }
;                     pr1[0] = r1[0]; pr1[1] = r1[1]; pr2[0] = r2[0]; pr2[1] = r2[1];
;                 }
.LBB0_930:
	s_or_b64 exec, exec, s[0:1]
	v_mov_b32_e32 v113, v112
	v_pk_mul_f32 v[42:43], v[12:13], v[112:113]
	v_mov_b32_e32 v24, v112
	v_mov_b32_e32 v25, v112
	v_mov_b32_dpp v30, v42 row_ror:1 row_mask:0xf bank_mask:0xf
	v_pk_mul_f32 v[40:41], v[14:15], v[24:25]
	v_mov_b32_dpp v31, v42 row_ror:2 row_mask:0xf bank_mask:0xf
	v_mov_b32_dpp v28, v43 row_ror:1 row_mask:0xf bank_mask:0xf
	v_cndmask_b32_e64 v38, v30, v38, s[8:9]
	v_mov_b32_dpp v29, v43 row_ror:2 row_mask:0xf bank_mask:0xf
	v_mov_b32_dpp v26, v40 row_ror:1 row_mask:0xf bank_mask:0xf
	v_cndmask_b32_e64 v39, v39, v31, s[10:11]
	v_fma_f32 v42, v96, v42, v100
	v_cndmask_b32_e64 v36, v28, v36, s[8:9]
	v_fma_f32 v38, v92, v38, v42
	v_pk_mul_f32 v[44:45], v[10:11], v[24:25]
	v_pk_mul_f32 v[46:47], v[8:9], v[112:113]
	v_mov_b32_dpp v27, v40 row_ror:2 row_mask:0xf bank_mask:0xf
	v_mov_b32_dpp v15, v41 row_ror:1 row_mask:0xf bank_mask:0xf
	v_fma_f32 v38, v88, v39, v38
	v_cndmask_b32_e64 v37, v37, v29, s[10:11]
	v_fma_f32 v39, v97, v43, v101
	v_cndmask_b32_e64 v34, v26, v34, s[8:9]
	v_fma_f32 v36, v93, v36, v39
	v_mov_b32_dpp v25, v41 row_ror:2 row_mask:0xf bank_mask:0xf
	v_mov_b32_dpp v14, v46 row_ror:1 row_mask:0xf bank_mask:0xf
	v_fma_f32 v36, v89, v37, v36
	v_cndmask_b32_e64 v35, v35, v27, s[10:11]
	v_fma_f32 v37, v98, v40, v102
	v_cndmask_b32_e64 v23, v15, v23, s[8:9]
	v_fma_f32 v34, v94, v34, v37
	v_mov_b32_dpp v24, v46 row_ror:2 row_mask:0xf bank_mask:0xf
	v_mov_b32_dpp v12, v47 row_ror:1 row_mask:0xf bank_mask:0xf
	v_fma_f32 v34, v90, v35, v34
	v_cndmask_b32_e64 v33, v33, v25, s[10:11]
	v_fma_f32 v35, v99, v41, v103
	v_cndmask_b32_e64 v22, v14, v22, s[8:9]
	v_fma_f32 v23, v95, v23, v35
	v_mov_b32_dpp v13, v47 row_ror:2 row_mask:0xf bank_mask:0xf
	v_mov_b32_dpp v10, v44 row_ror:1 row_mask:0xf bank_mask:0xf
	v_fma_f32 v23, v91, v33, v23
	v_cndmask_b32_e64 v32, v32, v24, s[10:11]
	v_fma_f32 v33, v80, v46, v84
	v_cndmask_b32_e64 v20, v12, v20, s[8:9]
	v_fma_f32 v22, v72, v22, v33
	v_mov_b32_dpp v11, v44 row_ror:2 row_mask:0xf bank_mask:0xf
	v_mov_b32_dpp v8, v45 row_ror:1 row_mask:0xf bank_mask:0xf
	v_fma_f32 v22, v68, v32, v22
	v_cndmask_b32_e64 v21, v21, v13, s[10:11]
	v_fma_f32 v32, v81, v47, v85
	v_cndmask_b32_e64 v18, v10, v18, s[8:9]
	v_fma_f32 v20, v73, v20, v32
	v_fma_f32 v20, v69, v21, v20
	v_cndmask_b32_e64 v19, v19, v11, s[10:11]
	v_fma_f32 v21, v82, v44, v86
	v_cndmask_b32_e64 v16, v8, v16, s[8:9]
	v_fma_f32 v18, v74, v18, v21
	v_mov_b32_dpp v9, v45 row_ror:2 row_mask:0xf bank_mask:0xf
	v_fma_f32 v18, v70, v19, v18
	v_fma_f32 v19, v83, v45, v87
	v_cndmask_b32_e64 v17, v17, v9, s[10:11]
	v_fma_f32 v16, v75, v16, v19
	s_nop 0
	v_fma_f32 v16, v71, v17, v16
	s_and_saveexec_b64 s[0:1], s[84:85]
	s_cbranch_execz .LBB0_932
	v_mul_f32_e32 v17, 0xbfb8aa3b, v23
	v_exp_f32_e32 v17, v17
	v_mul_f32_e32 v19, 0xbfb8aa3b, v34
	v_mul_f32_e32 v21, 0xbfb8aa3b, v36
	v_exp_f32_e32 v19, v19
	v_add_f32_e32 v17, 1.0, v17
	v_rcp_f32_e32 v17, v17
	v_exp_f32_e32 v21, v21
	v_add_f32_e32 v19, 1.0, v19
	v_rcp_f32_e32 v19, v19
	v_mul_f32_e32 v17, v23, v17
	v_mul_f32_e32 v17, v17, v16
	v_mul_f32_e32 v16, 0xbfb8aa3b, v38
	v_exp_f32_e32 v16, v16
	v_add_f32_e32 v21, 1.0, v21
	v_rcp_f32_e32 v21, v21
	v_mul_f32_e32 v19, v34, v19
	v_add_f32_e32 v16, 1.0, v16
	v_rcp_f32_e32 v16, v16
	v_mul_f32_e32 v18, v19, v18
	v_mul_f32_e32 v19, v36, v21
	v_mul_f32_e32 v19, v19, v20
	v_mul_f32_e32 v16, v38, v16
	v_mul_f32_e32 v16, v16, v22
	v_cvt_pk_bf16_f32 v16, v16, v19
	v_cvt_pk_bf16_f32 v17, v18, v17
	v_mul_u32_u24_e32 v18, s69, v114
	v_lshl_add_u32 v18, v192, 1, v18
	global_store_dwordx2 v18, v[16:17], s[36:37] offset:8
; __device__ __forceinline__ unsigned cvt_pk_bf16(float lo, float hi) { unsigned r; asm volatile("v_cvt_pk_bf16_f32 %0, %1, %2" : "=v"(r) : "v"(lo), "v"(hi)); return r; }
; __device__ __forceinline__ float sigmoid_f(float x) { return __builtin_amdgcn_rcpf(1.0f + __builtin_amdgcn_exp2f(-1.4426950408889634f * x)); }
; __device__ __forceinline__ float dpp_ror1(float v) { return __builtin_bit_cast(float, __builtin_amdgcn_update_dpp(0, __builtin_bit_cast(int, v), 0x121, 0xf, 0xf, false)); }
; __device__ __forceinline__ float dpp_ror2(float v) { return __builtin_bit_cast(float, __builtin_amdgcn_update_dpp(0, __builtin_bit_cast(int, v), 0x122, 0xf, 0xf, false)); }
; __device__ __forceinline__ float fma_s(float a, float b, float c) { float r; asm("v_fma_f32 %0, %1, %2, %3" : "=v"(r) : "v"(a), "v"(b), "v"(c)); return r; }
;     __device__ __forceinline__ void operator()(const f32x4 (&acc)[2][2][4][2], const Unit& u, int wr, int wc, int fr, int fq) const {
;     ...
;                 for (int m = 0; m < 4; ++m) {
;                     f32x4 cur[2] = {acc[ai][0][m][n] * r2v[ai][m], acc[ai][1][m][n] * r2v[ai][m]};
;                     if (first && ai == 0 && wr == 0 && m == 0 && fr < 2) { cur[0] = zero4; cur[1] = zero4; }
;                     f32x4 r1[2], r2[2], av[2];
; #pragma unroll
;                     for (int bj = 0; bj < 2; ++bj)
; #pragma unroll
;                         for (int e = 0; e < 4; ++e) { r1[bj][e] = dpp_ror1(cur[bj][e]); r2[bj][e] = dpp_ror2(cur[bj][e]); }
; #pragma unroll
;                     for (int bj = 0; bj < 2; ++bj)
; #pragma unroll
;                         for (int e = 0; e < 4; ++e) { const float p1 = fr >= 1 ? r1[bj][e] : pr1[bj][e], p2 = fr >= 2 ? r2[bj][e] : pr2[bj][e];
;                             av[bj][e] = fma_s(w0[bj][e], p2, fma_s(w1[bj][e], p1, fma_s(w2[bj][e], cur[bj][e], bb[bj][e]))); }
;                     float o[4];
; #pragma unroll
;                     for (int e = 0; e < 4; ++e) o[e] = av[0][e] * sigmoid_f(av[0][e]) * av[1][e];
;                     const int lr = ai * HALF + wr * 64 + m * 16 + fr, t = t0 + lr;
;                     if (lr >= 2 && t < 4096) { u32x2 w; w.x = cvt_pk_bf16(o[0], o[1]); w.y = cvt_pk_bf16(o[2], o[3]);
;                         *(u32x2*)(gout + (size_t)(b * 4096 + t) * FF + j0 + n * 4) = w; }
;                     pr1[0] = r1[0]; pr1[1] = r1[1]; pr2[0] = r2[0]; pr2[1] = r2[1];
;                 }
.LBB0_932:
	s_or_b64 exec, exec, s[0:1]
	v_mov_b32_e32 v195, v194
	v_pk_mul_f32 v[4:5], v[4:5], v[194:195]
	v_pk_mul_f32 v[18:19], v[0:1], v[194:195]
	v_mov_b32_e32 v16, v194
	v_mov_b32_e32 v17, v194
	v_mov_b32_dpp v0, v4 row_ror:1 row_mask:0xf bank_mask:0xf
	v_pk_mul_f32 v[6:7], v[6:7], v[16:17]
	v_pk_mul_f32 v[16:17], v[2:3], v[16:17]
	v_mov_b32_dpp v1, v4 row_ror:2 row_mask:0xf bank_mask:0xf
	v_cndmask_b32_e64 v0, v0, v30, s[8:9]
	v_mov_b32_dpp v2, v5 row_ror:1 row_mask:0xf bank_mask:0xf
	v_cndmask_b32_e64 v1, v31, v1, s[10:11]
	v_fma_f32 v4, v96, v4, v100
	v_mov_b32_dpp v3, v5 row_ror:2 row_mask:0xf bank_mask:0xf
	v_fma_f32 v0, v92, v0, v4
	v_fma_f32 v0, v88, v1, v0
	v_cndmask_b32_e64 v1, v2, v28, s[8:9]
	v_mov_b32_dpp v20, v6 row_ror:1 row_mask:0xf bank_mask:0xf
	v_cndmask_b32_e64 v2, v29, v3, s[10:11]
	v_fma_f32 v3, v97, v5, v101
	v_mov_b32_dpp v21, v6 row_ror:2 row_mask:0xf bank_mask:0xf
	v_fma_f32 v1, v93, v1, v3
	v_fma_f32 v1, v89, v2, v1
	v_cndmask_b32_e64 v2, v20, v26, s[8:9]
	v_mov_b32_dpp v22, v7 row_ror:1 row_mask:0xf bank_mask:0xf
	v_cndmask_b32_e64 v3, v27, v21, s[10:11]
	v_fma_f32 v4, v98, v6, v102
	v_mov_b32_dpp v23, v7 row_ror:2 row_mask:0xf bank_mask:0xf
	v_fma_f32 v2, v94, v2, v4
	v_fma_f32 v2, v90, v3, v2
	v_cndmask_b32_e64 v3, v22, v15, s[8:9]
	v_mov_b32_dpp v32, v18 row_ror:1 row_mask:0xf bank_mask:0xf
	v_cndmask_b32_e64 v4, v25, v23, s[10:11]
	v_fma_f32 v5, v99, v7, v103
	v_mov_b32_dpp v33, v18 row_ror:2 row_mask:0xf bank_mask:0xf
	v_fma_f32 v3, v95, v3, v5
	v_fma_f32 v4, v91, v4, v3
	v_cndmask_b32_e64 v3, v32, v14, s[8:9]
	v_mov_b32_dpp v34, v19 row_ror:1 row_mask:0xf bank_mask:0xf
	v_cndmask_b32_e64 v5, v24, v33, s[10:11]
	v_fma_f32 v6, v80, v18, v84
	v_mov_b32_dpp v35, v19 row_ror:2 row_mask:0xf bank_mask:0xf
	v_fma_f32 v3, v72, v3, v6
	v_fma_f32 v3, v68, v5, v3
	v_cndmask_b32_e64 v5, v34, v12, s[8:9]
	v_mov_b32_dpp v36, v16 row_ror:1 row_mask:0xf bank_mask:0xf
	v_cndmask_b32_e64 v6, v13, v35, s[10:11]
	v_fma_f32 v7, v81, v19, v85
	v_mov_b32_dpp v37, v16 row_ror:2 row_mask:0xf bank_mask:0xf
	v_fma_f32 v5, v73, v5, v7
	v_fma_f32 v5, v69, v6, v5
	v_cndmask_b32_e64 v6, v36, v10, s[8:9]
	v_mov_b32_dpp v38, v17 row_ror:1 row_mask:0xf bank_mask:0xf
	v_cndmask_b32_e64 v7, v11, v37, s[10:11]
	v_fma_f32 v10, v82, v16, v86
	v_mov_b32_dpp v39, v17 row_ror:2 row_mask:0xf bank_mask:0xf
	v_fma_f32 v6, v74, v6, v10
	s_nop 0
	v_fma_f32 v6, v70, v7, v6
	v_cndmask_b32_e64 v7, v38, v8, s[8:9]
	v_cndmask_b32_e64 v8, v9, v39, s[10:11]
	v_fma_f32 v9, v83, v17, v87
	s_nop 0
	v_fma_f32 v7, v75, v7, v9
	s_nop 0
	v_fma_f32 v7, v71, v8, v7
	s_and_saveexec_b64 s[0:1], s[86:87]
	s_cbranch_execz .LBB0_934
	v_mul_f32_e32 v8, 0xbfb8aa3b, v4
	v_exp_f32_e32 v8, v8
	v_mul_f32_e32 v9, 0xbfb8aa3b, v2
	v_mul_f32_e32 v10, 0xbfb8aa3b, v1
	v_exp_f32_e32 v9, v9
	v_add_f32_e32 v8, 1.0, v8
	v_rcp_f32_e32 v8, v8
	v_exp_f32_e32 v10, v10
	v_add_f32_e32 v9, 1.0, v9
	v_rcp_f32_e32 v9, v9
	v_mul_f32_e32 v4, v4, v8
	v_mul_f32_e32 v4, v4, v7
	v_mul_f32_e32 v7, 0xbfb8aa3b, v0
	v_exp_f32_e32 v7, v7
	v_add_f32_e32 v8, 1.0, v10
	v_rcp_f32_e32 v8, v8
	v_mul_f32_e32 v2, v2, v9
	v_add_f32_e32 v7, 1.0, v7
	v_rcp_f32_e32 v7, v7
	v_mul_f32_e32 v1, v1, v8
	v_mul_f32_e32 v2, v2, v6
	v_mul_f32_e32 v1, v1, v5
	v_mul_f32_e32 v0, v0, v7
	v_mul_f32_e32 v0, v0, v3
	v_cvt_pk_bf16_f32 v0, v0, v1
	v_cvt_pk_bf16_f32 v1, v2, v4
	v_mul_u32_u24_e32 v2, s69, v115
	v_lshl_add_u32 v2, v192, 1, v2
	global_store_dwordx2 v2, v[0:1], s[36:37] offset:8
